# phase 5 EpiMix: exponent argument as one fma against the pre-scaled bias row; separate copy for the first branch without old-sum loads
# speedup vs baseline: 1.0027x; 1.0027x over previous
; DI unsigned pack2(float a, float b) { fv2 v = {a, b}; return __builtin_bit_cast(unsigned, __builtin_convertvector(v, bfv2)); }
; DI float bflo(unsigned u) { return __uint_as_float(u << 16); }
; DI float bfhi(unsigned u) { return __uint_as_float(u & 0xffff0000u); }
; DI float sigmoidf_(float x) { return __builtin_amdgcn_rcpf(1.f + __expf(-x)); }
;   DI void operator()(const f32x4 (&acc)[2][2][4][2], const Unit& u, int wr, int wc, int fr, int fq) const {
;     const int row0 = u.pm * BM + wr * 64 + fr, col0 = u.pn * BM + wc * 32 + 8 * fq;
;     const char* sb = scr; asm volatile("" : "+s"(sb));
;     const unsigned toff = (unsigned)tidx() * 16u;
; #pragma unroll
;     for (int ai = 0; ai < 2; ++ai)
; #pragma unroll
;       for (int mp = 0; mp < 2; ++mp) {
;         u32x4 pv[2][2], ov[2][2];
;         f32x4 bv[2][2];
; #pragma unroll
;         for (int bj = 0; bj < 2; ++bj)
; #pragma unroll
;           for (int n = 0; n < 2; ++n) bv[bj][n] = *(const f32x4*)(bias + col0 + bj * HALF + 4 * n);
; #pragma unroll
;         for (int mm = 0; mm < 2; ++mm)
; #pragma unroll
;           for (int bj = 0; bj < 2; ++bj) {
;             const int m = mp * 2 + mm;
;             pv[mm][bj] = *(const u32x4*)(sb + (size_t)(((ai * 4 + m) * 2 + bj) * 8192) + toff);
;             ov[mm][bj] = (u32x4){0u, 0u, 0u, 0u};
;             if (!first) ov[mm][bj] = *(const u32x4*)(mixed + (size_t)(row0 + ai * HALF + m * 16) * 1024 + col0 + bj * HALF);
;           }
; #pragma unroll
;         for (int mm = 0; mm < 2; ++mm)
; #pragma unroll
;           for (int bj = 0; bj < 2; ++bj) {
;             const int m = mp * 2 + mm;
;             const f32x4 g0 = acc[ai][bj][m][0] + bv[bj][0], g1 = acc[ai][bj][m][1] + bv[bj][1];
;             const u32x4 p_ = pv[mm][bj], o_ = ov[mm][bj];
;             u32x4 w;
;             w.x = pack2(bflo(o_.x) + sigmoidf_(g0[0]) * bflo(p_.x), bfhi(o_.x) + sigmoidf_(g0[1]) * bfhi(p_.x));
;             w.y = pack2(bflo(o_.y) + sigmoidf_(g0[2]) * bflo(p_.y), bfhi(o_.y) + sigmoidf_(g0[3]) * bfhi(p_.y));
;             w.z = pack2(bflo(o_.z) + sigmoidf_(g1[0]) * bflo(p_.z), bfhi(o_.z) + sigmoidf_(g1[1]) * bfhi(p_.z));
;             w.w = pack2(bflo(o_.w) + sigmoidf_(g1[2]) * bflo(p_.w), bfhi(o_.w) + sigmoidf_(g1[3]) * bfhi(p_.w));
;             *(u32x4*)(mixed + (size_t)(row0 + ai * HALF + m * 16) * 1024 + col0 + bj * HALF) = w;
;           }
;       }
;   }
.LBB0_941:
.LBB0_942:
	s_lshl_b32 s0, s77, 9
	s_mov_b32 s1, s89
	s_and_b32 s0, s0, 0x7ffffc00
	s_lshl_b64 s[0:1], s[0:1], 2
	s_add_u32 s0, s70, s0
	s_addc_u32 s1, s71, s1
	v_lshrrev_b32_e32 v146, 1, v201
	v_and_b32_e32 v146, 24, v146
	v_or_b32_e32 v147, s76, v146
	v_lshlrev_b32_e32 v148, 2, v147
	global_load_dwordx4 v[130:133], v148, s[0:1]
	global_load_dwordx4 v[134:137], v148, s[0:1] offset:16
	global_load_dwordx4 v[138:141], v148, s[0:1] offset:512
	global_load_dwordx4 v[142:145], v148, s[0:1] offset:528
	v_lshlrev_b32_e32 v0, 4, v201
	v_and_b32_e32 v212, 15, v201
	v_lshlrev_b32_e32 v212, 11, v212
	v_lshl_add_u32 v212, v146, 1, v212
	s_lshl_b32 s98, s35, 11
	s_lshl_b32 s99, s76, 1
	s_add_u32 s98, s98, s99
	s_add_u32 s98, s2, s98
	s_addc_u32 s99, s3, 0
	s_cmp_lt_u32 s77, 2
	s_cbranch_scc1 .Lem_first
	s_mov_b64 s[6:7], s[8:9]
	s_mov_b64 s[100:101], s[98:99]
	global_load_dwordx4 v[166:169], v0, s[6:7]
	global_load_dwordx4 v[170:173], v212, s[98:99]
	s_add_u32 s6, s6, 0x2000
	s_addc_u32 s7, s7, 0
	global_load_dwordx4 v[174:177], v0, s[6:7]
	global_load_dwordx4 v[184:187], v212, s[98:99] offset:256
	s_add_u32 s6, s6, 0x2000
	s_addc_u32 s7, s7, 0
	s_add_u32 s98, s98, 0x8000
	s_addc_u32 s99, s99, 0
	global_load_dwordx4 v[188:191], v0, s[6:7]
	global_load_dwordx4 v[192:195], v212, s[98:99]
	s_add_u32 s6, s6, 0x2000
	s_addc_u32 s7, s7, 0
	s_waitcnt vmcnt(6)
	v_mul_f32_e32 v130, 0xbfb8aa3b, v130
	v_mul_f32_e32 v131, 0xbfb8aa3b, v131
	v_mul_f32_e32 v132, 0xbfb8aa3b, v132
	v_mul_f32_e32 v133, 0xbfb8aa3b, v133
	v_mul_f32_e32 v134, 0xbfb8aa3b, v134
	v_mul_f32_e32 v135, 0xbfb8aa3b, v135
	v_mul_f32_e32 v136, 0xbfb8aa3b, v136
	v_mul_f32_e32 v137, 0xbfb8aa3b, v137
	v_mul_f32_e32 v138, 0xbfb8aa3b, v138
	v_mul_f32_e32 v139, 0xbfb8aa3b, v139
	v_mul_f32_e32 v140, 0xbfb8aa3b, v140
	v_mul_f32_e32 v141, 0xbfb8aa3b, v141
	v_mul_f32_e32 v142, 0xbfb8aa3b, v142
	v_mul_f32_e32 v143, 0xbfb8aa3b, v143
	v_mul_f32_e32 v144, 0xbfb8aa3b, v144
	v_mul_f32_e32 v145, 0xbfb8aa3b, v145
	v_fmamk_f32 v146, v126, 0xbfb8aa3b, v130
	v_fmamk_f32 v147, v127, 0xbfb8aa3b, v131
	v_fmamk_f32 v148, v128, 0xbfb8aa3b, v132
	v_fmamk_f32 v149, v129, 0xbfb8aa3b, v133
	v_fmamk_f32 v150, v122, 0xbfb8aa3b, v134
	v_fmamk_f32 v151, v123, 0xbfb8aa3b, v135
	v_fmamk_f32 v152, v124, 0xbfb8aa3b, v136
	v_fmamk_f32 v153, v125, 0xbfb8aa3b, v137
	v_exp_f32_e32 v146, v146
	v_exp_f32_e32 v147, v147
	v_exp_f32_e32 v148, v148
	v_exp_f32_e32 v149, v149
	v_exp_f32_e32 v150, v150
	v_exp_f32_e32 v151, v151
	v_exp_f32_e32 v152, v152
	v_exp_f32_e32 v153, v153
	s_waitcnt vmcnt(4)
	v_lshlrev_b32_e32 v126, 16, v166
	v_and_b32_e32 v127, 0xffff0000, v166
	v_lshlrev_b32_e32 v128, 16, v167
	v_and_b32_e32 v129, 0xffff0000, v167
	v_lshlrev_b32_e32 v122, 16, v168
	v_and_b32_e32 v123, 0xffff0000, v168
	v_lshlrev_b32_e32 v124, 16, v169
	v_and_b32_e32 v125, 0xffff0000, v169
	v_add_f32_e32 v146, 1.0, v146
	v_add_f32_e32 v147, 1.0, v147
	v_add_f32_e32 v148, 1.0, v148
	v_add_f32_e32 v149, 1.0, v149
	v_add_f32_e32 v150, 1.0, v150
	v_add_f32_e32 v151, 1.0, v151
	v_add_f32_e32 v152, 1.0, v152
	v_add_f32_e32 v153, 1.0, v153
	v_rcp_f32_e32 v146, v146
	v_rcp_f32_e32 v147, v147
	v_rcp_f32_e32 v148, v148
	v_rcp_f32_e32 v149, v149
	v_rcp_f32_e32 v150, v150
	v_rcp_f32_e32 v151, v151
	v_rcp_f32_e32 v152, v152
	v_rcp_f32_e32 v153, v153
	v_lshlrev_b32_e32 v154, 16, v170
	v_and_b32_e32 v155, 0xffff0000, v170
	v_lshlrev_b32_e32 v156, 16, v171
	v_and_b32_e32 v157, 0xffff0000, v171
	v_lshlrev_b32_e32 v158, 16, v172
	v_and_b32_e32 v159, 0xffff0000, v172
	v_lshlrev_b32_e32 v160, 16, v173
	v_and_b32_e32 v161, 0xffff0000, v173
	v_pk_fma_f32 v[146:147], v[146:147], v[126:127], v[154:155]
	v_pk_fma_f32 v[148:149], v[148:149], v[128:129], v[156:157]
	v_pk_fma_f32 v[150:151], v[150:151], v[122:123], v[158:159]
	v_pk_fma_f32 v[152:153], v[152:153], v[124:125], v[160:161]
	v_cvt_pk_bf16_f32 v162, v146, v147
	v_cvt_pk_bf16_f32 v163, v148, v149
	v_cvt_pk_bf16_f32 v164, v150, v151
	v_cvt_pk_bf16_f32 v165, v152, v153
	global_store_dwordx4 v212, v[162:165], s[100:101]
	global_load_dwordx4 v[196:199], v0, s[6:7]
	global_load_dwordx4 v[166:169], v212, s[98:99] offset:256
	s_add_u32 s6, s6, 0x2000
	s_addc_u32 s7, s7, 0
	s_add_u32 s98, s98, 0x8000
	s_addc_u32 s99, s99, 0
	global_load_dwordx4 v[126:129], v0, s[6:7]
	global_load_dwordx4 v[122:125], v212, s[98:99]
	s_add_u32 s6, s6, 0x2000
	s_addc_u32 s7, s7, 0
	v_fmamk_f32 v146, v118, 0xbfb8aa3b, v138
	v_fmamk_f32 v147, v119, 0xbfb8aa3b, v139
	v_fmamk_f32 v148, v120, 0xbfb8aa3b, v140
	v_fmamk_f32 v149, v121, 0xbfb8aa3b, v141
	v_fmamk_f32 v150, v114, 0xbfb8aa3b, v142
	v_fmamk_f32 v151, v115, 0xbfb8aa3b, v143
	v_fmamk_f32 v152, v116, 0xbfb8aa3b, v144
	v_fmamk_f32 v153, v117, 0xbfb8aa3b, v145
	v_exp_f32_e32 v146, v146
	v_exp_f32_e32 v147, v147
	v_exp_f32_e32 v148, v148
	v_exp_f32_e32 v149, v149
	v_exp_f32_e32 v150, v150
	v_exp_f32_e32 v151, v151
	v_exp_f32_e32 v152, v152
	v_exp_f32_e32 v153, v153
	s_waitcnt vmcnt(7)
; DI unsigned pack2(float a, float b) { fv2 v = {a, b}; return __builtin_bit_cast(unsigned, __builtin_convertvector(v, bfv2)); }
; DI float bflo(unsigned u) { return __uint_as_float(u << 16); }
; DI float bfhi(unsigned u) { return __uint_as_float(u & 0xffff0000u); }
; DI float sigmoidf_(float x) { return __builtin_amdgcn_rcpf(1.f + __expf(-x)); }
;   DI void operator()(const f32x4 (&acc)[2][2][4][2], const Unit& u, int wr, int wc, int fr, int fq) const {
;     ...
; #pragma unroll
;           for (int n = 0; n < 2; ++n) bv[bj][n] = *(const f32x4*)(bias + col0 + bj * HALF + 4 * n);
; #pragma unroll
;         for (int mm = 0; mm < 2; ++mm)
; #pragma unroll
;           for (int bj = 0; bj < 2; ++bj) {
;             const int m = mp * 2 + mm;
;             pv[mm][bj] = *(const u32x4*)(sb + (size_t)(((ai * 4 + m) * 2 + bj) * 8192) + toff);
;             ov[mm][bj] = (u32x4){0u, 0u, 0u, 0u};
;             if (!first) ov[mm][bj] = *(const u32x4*)(mixed + (size_t)(row0 + ai * HALF + m * 16) * 1024 + col0 + bj * HALF);
;           }
; #pragma unroll
;         for (int mm = 0; mm < 2; ++mm)
; #pragma unroll
;           for (int bj = 0; bj < 2; ++bj) {
;             const int m = mp * 2 + mm;
;             const f32x4 g0 = acc[ai][bj][m][0] + bv[bj][0], g1 = acc[ai][bj][m][1] + bv[bj][1];
;             const u32x4 p_ = pv[mm][bj], o_ = ov[mm][bj];
;             u32x4 w;
;             w.x = pack2(bflo(o_.x) + sigmoidf_(g0[0]) * bflo(p_.x), bfhi(o_.x) + sigmoidf_(g0[1]) * bfhi(p_.x));
;             w.y = pack2(bflo(o_.y) + sigmoidf_(g0[2]) * bflo(p_.y), bfhi(o_.y) + sigmoidf_(g0[3]) * bfhi(p_.y));
;             w.z = pack2(bflo(o_.z) + sigmoidf_(g1[0]) * bflo(p_.z), bfhi(o_.z) + sigmoidf_(g1[1]) * bfhi(p_.z));
;             w.w = pack2(bflo(o_.w) + sigmoidf_(g1[2]) * bflo(p_.w), bfhi(o_.w) + sigmoidf_(g1[3]) * bfhi(p_.w));
;             *(u32x4*)(mixed + (size_t)(row0 + ai * HALF + m * 16) * 1024 + col0 + bj * HALF) = w;
	v_lshlrev_b32_e32 v118, 16, v174
	v_and_b32_e32 v119, 0xffff0000, v174
	v_lshlrev_b32_e32 v120, 16, v175
	v_and_b32_e32 v121, 0xffff0000, v175
	v_lshlrev_b32_e32 v114, 16, v176
	v_and_b32_e32 v115, 0xffff0000, v176
	v_lshlrev_b32_e32 v116, 16, v177
	v_and_b32_e32 v117, 0xffff0000, v177
	v_add_f32_e32 v146, 1.0, v146
	v_add_f32_e32 v147, 1.0, v147
	v_add_f32_e32 v148, 1.0, v148
	v_add_f32_e32 v149, 1.0, v149
	v_add_f32_e32 v150, 1.0, v150
	v_add_f32_e32 v151, 1.0, v151
	v_add_f32_e32 v152, 1.0, v152
	v_add_f32_e32 v153, 1.0, v153
	v_rcp_f32_e32 v146, v146
	v_rcp_f32_e32 v147, v147
	v_rcp_f32_e32 v148, v148
	v_rcp_f32_e32 v149, v149
	v_rcp_f32_e32 v150, v150
	v_rcp_f32_e32 v151, v151
	v_rcp_f32_e32 v152, v152
	v_rcp_f32_e32 v153, v153
	v_lshlrev_b32_e32 v154, 16, v184
	v_and_b32_e32 v155, 0xffff0000, v184
	v_lshlrev_b32_e32 v156, 16, v185
	v_and_b32_e32 v157, 0xffff0000, v185
	v_lshlrev_b32_e32 v158, 16, v186
	v_and_b32_e32 v159, 0xffff0000, v186
	v_lshlrev_b32_e32 v160, 16, v187
	v_and_b32_e32 v161, 0xffff0000, v187
	v_pk_fma_f32 v[146:147], v[146:147], v[118:119], v[154:155]
	v_pk_fma_f32 v[148:149], v[148:149], v[120:121], v[156:157]
	v_pk_fma_f32 v[150:151], v[150:151], v[114:115], v[158:159]
	v_pk_fma_f32 v[152:153], v[152:153], v[116:117], v[160:161]
	v_cvt_pk_bf16_f32 v162, v146, v147
	v_cvt_pk_bf16_f32 v163, v148, v149
	v_cvt_pk_bf16_f32 v164, v150, v151
	v_cvt_pk_bf16_f32 v165, v152, v153
	global_store_dwordx4 v212, v[162:165], s[100:101] offset:256
	s_add_u32 s100, s100, 0x8000
	s_addc_u32 s101, s101, 0
	global_load_dwordx4 v[170:173], v0, s[6:7]
	global_load_dwordx4 v[174:177], v212, s[98:99] offset:256
	s_add_u32 s6, s6, 0x2000
	s_addc_u32 s7, s7, 0
	s_add_u32 s98, s98, 0x8000
	s_addc_u32 s99, s99, 0
	global_load_dwordx4 v[118:121], v0, s[6:7]
	global_load_dwordx4 v[114:117], v212, s[98:99]
	s_add_u32 s6, s6, 0x2000
	s_addc_u32 s7, s7, 0
	v_fmamk_f32 v146, v110, 0xbfb8aa3b, v130
	v_fmamk_f32 v147, v111, 0xbfb8aa3b, v131
	v_fmamk_f32 v148, v112, 0xbfb8aa3b, v132
	v_fmamk_f32 v149, v113, 0xbfb8aa3b, v133
	v_fmamk_f32 v150, v106, 0xbfb8aa3b, v134
	v_fmamk_f32 v151, v107, 0xbfb8aa3b, v135
	v_fmamk_f32 v152, v108, 0xbfb8aa3b, v136
	v_fmamk_f32 v153, v109, 0xbfb8aa3b, v137
	v_exp_f32_e32 v146, v146
	v_exp_f32_e32 v147, v147
	v_exp_f32_e32 v148, v148
	v_exp_f32_e32 v149, v149
	v_exp_f32_e32 v150, v150
	v_exp_f32_e32 v151, v151
	v_exp_f32_e32 v152, v152
	v_exp_f32_e32 v153, v153
	s_waitcnt vmcnt(10)
	v_lshlrev_b32_e32 v110, 16, v188
	v_and_b32_e32 v111, 0xffff0000, v188
	v_lshlrev_b32_e32 v112, 16, v189
	v_and_b32_e32 v113, 0xffff0000, v189
	v_lshlrev_b32_e32 v106, 16, v190
	v_and_b32_e32 v107, 0xffff0000, v190
	v_lshlrev_b32_e32 v108, 16, v191
	v_and_b32_e32 v109, 0xffff0000, v191
	v_add_f32_e32 v146, 1.0, v146
	v_add_f32_e32 v147, 1.0, v147
	v_add_f32_e32 v148, 1.0, v148
	v_add_f32_e32 v149, 1.0, v149
	v_add_f32_e32 v150, 1.0, v150
	v_add_f32_e32 v151, 1.0, v151
	v_add_f32_e32 v152, 1.0, v152
	v_add_f32_e32 v153, 1.0, v153
	v_rcp_f32_e32 v146, v146
	v_rcp_f32_e32 v147, v147
	v_rcp_f32_e32 v148, v148
	v_rcp_f32_e32 v149, v149
	v_rcp_f32_e32 v150, v150
	v_rcp_f32_e32 v151, v151
	v_rcp_f32_e32 v152, v152
	v_rcp_f32_e32 v153, v153
	v_lshlrev_b32_e32 v154, 16, v192
	v_and_b32_e32 v155, 0xffff0000, v192
	v_lshlrev_b32_e32 v156, 16, v193
	v_and_b32_e32 v157, 0xffff0000, v193
	v_lshlrev_b32_e32 v158, 16, v194
	v_and_b32_e32 v159, 0xffff0000, v194
	v_lshlrev_b32_e32 v160, 16, v195
	v_and_b32_e32 v161, 0xffff0000, v195
	v_pk_fma_f32 v[146:147], v[146:147], v[110:111], v[154:155]
	v_pk_fma_f32 v[148:149], v[148:149], v[112:113], v[156:157]
	v_pk_fma_f32 v[150:151], v[150:151], v[106:107], v[158:159]
	v_pk_fma_f32 v[152:153], v[152:153], v[108:109], v[160:161]
	v_cvt_pk_bf16_f32 v162, v146, v147
	v_cvt_pk_bf16_f32 v163, v148, v149
	v_cvt_pk_bf16_f32 v164, v150, v151
	v_cvt_pk_bf16_f32 v165, v152, v153
	global_store_dwordx4 v212, v[162:165], s[100:101]
	global_load_dwordx4 v[184:187], v0, s[6:7]
	global_load_dwordx4 v[188:191], v212, s[98:99] offset:256
	s_add_u32 s6, s6, 0x2000
	s_addc_u32 s7, s7, 0
	s_add_u32 s98, s98, 0x28000
	s_addc_u32 s99, s99, 0
	global_load_dwordx4 v[110:113], v0, s[6:7]
	global_load_dwordx4 v[106:109], v212, s[98:99]
	s_add_u32 s6, s6, 0x2000
	s_addc_u32 s7, s7, 0
	v_fmamk_f32 v146, v102, 0xbfb8aa3b, v138
	v_fmamk_f32 v147, v103, 0xbfb8aa3b, v139
	v_fmamk_f32 v148, v104, 0xbfb8aa3b, v140
	v_fmamk_f32 v149, v105, 0xbfb8aa3b, v141
	v_fmamk_f32 v150, v98, 0xbfb8aa3b, v142
	v_fmamk_f32 v151, v99, 0xbfb8aa3b, v143
	v_fmamk_f32 v152, v100, 0xbfb8aa3b, v144
	v_fmamk_f32 v153, v101, 0xbfb8aa3b, v145
	v_exp_f32_e32 v146, v146
	v_exp_f32_e32 v147, v147
	v_exp_f32_e32 v148, v148
	v_exp_f32_e32 v149, v149
	v_exp_f32_e32 v150, v150
	v_exp_f32_e32 v151, v151
	v_exp_f32_e32 v152, v152
	v_exp_f32_e32 v153, v153
	s_waitcnt vmcnt(12)
; DI unsigned pack2(float a, float b) { fv2 v = {a, b}; return __builtin_bit_cast(unsigned, __builtin_convertvector(v, bfv2)); }
; DI float bflo(unsigned u) { return __uint_as_float(u << 16); }
; DI float bfhi(unsigned u) { return __uint_as_float(u & 0xffff0000u); }
; DI float sigmoidf_(float x) { return __builtin_amdgcn_rcpf(1.f + __expf(-x)); }
;   DI void operator()(const f32x4 (&acc)[2][2][4][2], const Unit& u, int wr, int wc, int fr, int fq) const {
;     ...
; #pragma unroll
;           for (int n = 0; n < 2; ++n) bv[bj][n] = *(const f32x4*)(bias + col0 + bj * HALF + 4 * n);
; #pragma unroll
;         for (int mm = 0; mm < 2; ++mm)
; #pragma unroll
;           for (int bj = 0; bj < 2; ++bj) {
;             const int m = mp * 2 + mm;
;             pv[mm][bj] = *(const u32x4*)(sb + (size_t)(((ai * 4 + m) * 2 + bj) * 8192) + toff);
;             ov[mm][bj] = (u32x4){0u, 0u, 0u, 0u};
;             if (!first) ov[mm][bj] = *(const u32x4*)(mixed + (size_t)(row0 + ai * HALF + m * 16) * 1024 + col0 + bj * HALF);
;           }
; #pragma unroll
;         for (int mm = 0; mm < 2; ++mm)
; #pragma unroll
;           for (int bj = 0; bj < 2; ++bj) {
;             const int m = mp * 2 + mm;
;             const f32x4 g0 = acc[ai][bj][m][0] + bv[bj][0], g1 = acc[ai][bj][m][1] + bv[bj][1];
;             const u32x4 p_ = pv[mm][bj], o_ = ov[mm][bj];
;             u32x4 w;
;             w.x = pack2(bflo(o_.x) + sigmoidf_(g0[0]) * bflo(p_.x), bfhi(o_.x) + sigmoidf_(g0[1]) * bfhi(p_.x));
;             w.y = pack2(bflo(o_.y) + sigmoidf_(g0[2]) * bflo(p_.y), bfhi(o_.y) + sigmoidf_(g0[3]) * bfhi(p_.y));
;             w.z = pack2(bflo(o_.z) + sigmoidf_(g1[0]) * bflo(p_.z), bfhi(o_.z) + sigmoidf_(g1[1]) * bfhi(p_.z));
;             w.w = pack2(bflo(o_.w) + sigmoidf_(g1[2]) * bflo(p_.w), bfhi(o_.w) + sigmoidf_(g1[3]) * bfhi(p_.w));
;             *(u32x4*)(mixed + (size_t)(row0 + ai * HALF + m * 16) * 1024 + col0 + bj * HALF) = w;
	v_lshlrev_b32_e32 v102, 16, v196
	v_and_b32_e32 v103, 0xffff0000, v196
	v_lshlrev_b32_e32 v104, 16, v197
	v_and_b32_e32 v105, 0xffff0000, v197
	v_lshlrev_b32_e32 v98, 16, v198
	v_and_b32_e32 v99, 0xffff0000, v198
	v_lshlrev_b32_e32 v100, 16, v199
	v_and_b32_e32 v101, 0xffff0000, v199
	v_add_f32_e32 v146, 1.0, v146
	v_add_f32_e32 v147, 1.0, v147
	v_add_f32_e32 v148, 1.0, v148
	v_add_f32_e32 v149, 1.0, v149
	v_add_f32_e32 v150, 1.0, v150
	v_add_f32_e32 v151, 1.0, v151
	v_add_f32_e32 v152, 1.0, v152
	v_add_f32_e32 v153, 1.0, v153
	v_rcp_f32_e32 v146, v146
	v_rcp_f32_e32 v147, v147
	v_rcp_f32_e32 v148, v148
	v_rcp_f32_e32 v149, v149
	v_rcp_f32_e32 v150, v150
	v_rcp_f32_e32 v151, v151
	v_rcp_f32_e32 v152, v152
	v_rcp_f32_e32 v153, v153
	v_lshlrev_b32_e32 v154, 16, v166
	v_and_b32_e32 v155, 0xffff0000, v166
	v_lshlrev_b32_e32 v156, 16, v167
	v_and_b32_e32 v157, 0xffff0000, v167
	v_lshlrev_b32_e32 v158, 16, v168
	v_and_b32_e32 v159, 0xffff0000, v168
	v_lshlrev_b32_e32 v160, 16, v169
	v_and_b32_e32 v161, 0xffff0000, v169
	v_pk_fma_f32 v[146:147], v[146:147], v[102:103], v[154:155]
	v_pk_fma_f32 v[148:149], v[148:149], v[104:105], v[156:157]
	v_pk_fma_f32 v[150:151], v[150:151], v[98:99], v[158:159]
	v_pk_fma_f32 v[152:153], v[152:153], v[100:101], v[160:161]
	v_cvt_pk_bf16_f32 v162, v146, v147
	v_cvt_pk_bf16_f32 v163, v148, v149
	v_cvt_pk_bf16_f32 v164, v150, v151
	v_cvt_pk_bf16_f32 v165, v152, v153
	global_store_dwordx4 v212, v[162:165], s[100:101] offset:256
	s_add_u32 s100, s100, 0x8000
	s_addc_u32 s101, s101, 0
	global_load_dwordx4 v[192:195], v0, s[6:7]
	global_load_dwordx4 v[196:199], v212, s[98:99] offset:256
	s_add_u32 s6, s6, 0x2000
	s_addc_u32 s7, s7, 0
	s_add_u32 s98, s98, 0x8000
	s_addc_u32 s99, s99, 0
	v_fmamk_f32 v146, v94, 0xbfb8aa3b, v130
	v_fmamk_f32 v147, v95, 0xbfb8aa3b, v131
	v_fmamk_f32 v148, v96, 0xbfb8aa3b, v132
	v_fmamk_f32 v149, v97, 0xbfb8aa3b, v133
	v_fmamk_f32 v150, v90, 0xbfb8aa3b, v134
	v_fmamk_f32 v151, v91, 0xbfb8aa3b, v135
	v_fmamk_f32 v152, v92, 0xbfb8aa3b, v136
	v_fmamk_f32 v153, v93, 0xbfb8aa3b, v137
	v_exp_f32_e32 v146, v146
	v_exp_f32_e32 v147, v147
	v_exp_f32_e32 v148, v148
	v_exp_f32_e32 v149, v149
	v_exp_f32_e32 v150, v150
	v_exp_f32_e32 v151, v151
	v_exp_f32_e32 v152, v152
	v_exp_f32_e32 v153, v153
	s_waitcnt vmcnt(13)
	v_lshlrev_b32_e32 v94, 16, v126
	v_and_b32_e32 v95, 0xffff0000, v126
	v_lshlrev_b32_e32 v96, 16, v127
	v_and_b32_e32 v97, 0xffff0000, v127
	v_lshlrev_b32_e32 v90, 16, v128
	v_and_b32_e32 v91, 0xffff0000, v128
	v_lshlrev_b32_e32 v92, 16, v129
	v_and_b32_e32 v93, 0xffff0000, v129
	v_add_f32_e32 v146, 1.0, v146
	v_add_f32_e32 v147, 1.0, v147
	v_add_f32_e32 v148, 1.0, v148
	v_add_f32_e32 v149, 1.0, v149
	v_add_f32_e32 v150, 1.0, v150
	v_add_f32_e32 v151, 1.0, v151
	v_add_f32_e32 v152, 1.0, v152
	v_add_f32_e32 v153, 1.0, v153
	v_rcp_f32_e32 v146, v146
	v_rcp_f32_e32 v147, v147
	v_rcp_f32_e32 v148, v148
	v_rcp_f32_e32 v149, v149
	v_rcp_f32_e32 v150, v150
	v_rcp_f32_e32 v151, v151
	v_rcp_f32_e32 v152, v152
	v_rcp_f32_e32 v153, v153
	v_lshlrev_b32_e32 v154, 16, v122
	v_and_b32_e32 v155, 0xffff0000, v122
	v_lshlrev_b32_e32 v156, 16, v123
	v_and_b32_e32 v157, 0xffff0000, v123
	v_lshlrev_b32_e32 v158, 16, v124
	v_and_b32_e32 v159, 0xffff0000, v124
	v_lshlrev_b32_e32 v160, 16, v125
	v_and_b32_e32 v161, 0xffff0000, v125
	v_pk_fma_f32 v[146:147], v[146:147], v[94:95], v[154:155]
	v_pk_fma_f32 v[148:149], v[148:149], v[96:97], v[156:157]
	v_pk_fma_f32 v[150:151], v[150:151], v[90:91], v[158:159]
	v_pk_fma_f32 v[152:153], v[152:153], v[92:93], v[160:161]
	v_cvt_pk_bf16_f32 v162, v146, v147
	v_cvt_pk_bf16_f32 v163, v148, v149
	v_cvt_pk_bf16_f32 v164, v150, v151
	v_cvt_pk_bf16_f32 v165, v152, v153
	global_store_dwordx4 v212, v[162:165], s[100:101]
	global_load_dwordx4 v[102:105], v0, s[6:7]
	global_load_dwordx4 v[98:101], v212, s[98:99]
	s_add_u32 s6, s6, 0x2000
	s_addc_u32 s7, s7, 0
	v_fmamk_f32 v146, v86, 0xbfb8aa3b, v138
	v_fmamk_f32 v147, v87, 0xbfb8aa3b, v139
	v_fmamk_f32 v148, v88, 0xbfb8aa3b, v140
	v_fmamk_f32 v149, v89, 0xbfb8aa3b, v141
	v_fmamk_f32 v150, v82, 0xbfb8aa3b, v142
	v_fmamk_f32 v151, v83, 0xbfb8aa3b, v143
	v_fmamk_f32 v152, v84, 0xbfb8aa3b, v144
	v_fmamk_f32 v153, v85, 0xbfb8aa3b, v145
	v_exp_f32_e32 v146, v146
	v_exp_f32_e32 v147, v147
	v_exp_f32_e32 v148, v148
	v_exp_f32_e32 v149, v149
	v_exp_f32_e32 v150, v150
	v_exp_f32_e32 v151, v151
	v_exp_f32_e32 v152, v152
	v_exp_f32_e32 v153, v153
	s_waitcnt vmcnt(13)
	v_lshlrev_b32_e32 v86, 16, v170
	v_and_b32_e32 v87, 0xffff0000, v170
	v_lshlrev_b32_e32 v88, 16, v171
	v_and_b32_e32 v89, 0xffff0000, v171
	v_lshlrev_b32_e32 v82, 16, v172
	v_and_b32_e32 v83, 0xffff0000, v172
	v_lshlrev_b32_e32 v84, 16, v173
	v_and_b32_e32 v85, 0xffff0000, v173
	v_add_f32_e32 v146, 1.0, v146
	v_add_f32_e32 v147, 1.0, v147
	v_add_f32_e32 v148, 1.0, v148
	v_add_f32_e32 v149, 1.0, v149
	v_add_f32_e32 v150, 1.0, v150
	v_add_f32_e32 v151, 1.0, v151
	v_add_f32_e32 v152, 1.0, v152
	v_add_f32_e32 v153, 1.0, v153
	v_rcp_f32_e32 v146, v146
	v_rcp_f32_e32 v147, v147
	v_rcp_f32_e32 v148, v148
	v_rcp_f32_e32 v149, v149
	v_rcp_f32_e32 v150, v150
	v_rcp_f32_e32 v151, v151
	v_rcp_f32_e32 v152, v152
	v_rcp_f32_e32 v153, v153
	v_lshlrev_b32_e32 v154, 16, v174
	v_and_b32_e32 v155, 0xffff0000, v174
	v_lshlrev_b32_e32 v156, 16, v175
	v_and_b32_e32 v157, 0xffff0000, v175
	v_lshlrev_b32_e32 v158, 16, v176
	v_and_b32_e32 v159, 0xffff0000, v176
	v_lshlrev_b32_e32 v160, 16, v177
	v_and_b32_e32 v161, 0xffff0000, v177
	v_pk_fma_f32 v[146:147], v[146:147], v[86:87], v[154:155]
	v_pk_fma_f32 v[148:149], v[148:149], v[88:89], v[156:157]
	v_pk_fma_f32 v[150:151], v[150:151], v[82:83], v[158:159]
	v_pk_fma_f32 v[152:153], v[152:153], v[84:85], v[160:161]
	v_cvt_pk_bf16_f32 v162, v146, v147
	v_cvt_pk_bf16_f32 v163, v148, v149
	v_cvt_pk_bf16_f32 v164, v150, v151
	v_cvt_pk_bf16_f32 v165, v152, v153
	global_store_dwordx4 v212, v[162:165], s[100:101] offset:256
	s_add_u32 s100, s100, 0x8000
	s_addc_u32 s101, s101, 0
	global_load_dwordx4 v[166:169], v0, s[6:7]
	global_load_dwordx4 v[126:129], v212, s[98:99] offset:256
	s_add_u32 s6, s6, 0x2000
	s_addc_u32 s7, s7, 0
	s_add_u32 s98, s98, 0x8000
	s_addc_u32 s99, s99, 0
	v_fmamk_f32 v146, v78, 0xbfb8aa3b, v130
	v_fmamk_f32 v147, v79, 0xbfb8aa3b, v131
	v_fmamk_f32 v148, v80, 0xbfb8aa3b, v132
	v_fmamk_f32 v149, v81, 0xbfb8aa3b, v133
	v_fmamk_f32 v150, v74, 0xbfb8aa3b, v134
	v_fmamk_f32 v151, v75, 0xbfb8aa3b, v135
	v_fmamk_f32 v152, v76, 0xbfb8aa3b, v136
	v_fmamk_f32 v153, v77, 0xbfb8aa3b, v137
	v_exp_f32_e32 v146, v146
	v_exp_f32_e32 v147, v147
	v_exp_f32_e32 v148, v148
	v_exp_f32_e32 v149, v149
	v_exp_f32_e32 v150, v150
	v_exp_f32_e32 v151, v151
	v_exp_f32_e32 v152, v152
	v_exp_f32_e32 v153, v153
	s_waitcnt vmcnt(14)
; DI unsigned pack2(float a, float b) { fv2 v = {a, b}; return __builtin_bit_cast(unsigned, __builtin_convertvector(v, bfv2)); }
; DI float bflo(unsigned u) { return __uint_as_float(u << 16); }
; DI float bfhi(unsigned u) { return __uint_as_float(u & 0xffff0000u); }
; DI float sigmoidf_(float x) { return __builtin_amdgcn_rcpf(1.f + __expf(-x)); }
;   DI void operator()(const f32x4 (&acc)[2][2][4][2], const Unit& u, int wr, int wc, int fr, int fq) const {
;     ...
; #pragma unroll
;     for (int ai = 0; ai < 2; ++ai)
; #pragma unroll
;       for (int mp = 0; mp < 2; ++mp) {
;         u32x4 pv[2][2], ov[2][2];
;         f32x4 bv[2][2];
; #pragma unroll
;         for (int bj = 0; bj < 2; ++bj)
; #pragma unroll
;           for (int n = 0; n < 2; ++n) bv[bj][n] = *(const f32x4*)(bias + col0 + bj * HALF + 4 * n);
; #pragma unroll
;         for (int mm = 0; mm < 2; ++mm)
; #pragma unroll
;           for (int bj = 0; bj < 2; ++bj) {
;             const int m = mp * 2 + mm;
;             pv[mm][bj] = *(const u32x4*)(sb + (size_t)(((ai * 4 + m) * 2 + bj) * 8192) + toff);
;             ov[mm][bj] = (u32x4){0u, 0u, 0u, 0u};
;             if (!first) ov[mm][bj] = *(const u32x4*)(mixed + (size_t)(row0 + ai * HALF + m * 16) * 1024 + col0 + bj * HALF);
;           }
; #pragma unroll
;         for (int mm = 0; mm < 2; ++mm)
; #pragma unroll
;           for (int bj = 0; bj < 2; ++bj) {
;             const int m = mp * 2 + mm;
;             const f32x4 g0 = acc[ai][bj][m][0] + bv[bj][0], g1 = acc[ai][bj][m][1] + bv[bj][1];
;             const u32x4 p_ = pv[mm][bj], o_ = ov[mm][bj];
;             u32x4 w;
;             w.x = pack2(bflo(o_.x) + sigmoidf_(g0[0]) * bflo(p_.x), bfhi(o_.x) + sigmoidf_(g0[1]) * bfhi(p_.x));
;             w.y = pack2(bflo(o_.y) + sigmoidf_(g0[2]) * bflo(p_.y), bfhi(o_.y) + sigmoidf_(g0[3]) * bfhi(p_.y));
;             w.z = pack2(bflo(o_.z) + sigmoidf_(g1[0]) * bflo(p_.z), bfhi(o_.z) + sigmoidf_(g1[1]) * bfhi(p_.z));
;             w.w = pack2(bflo(o_.w) + sigmoidf_(g1[2]) * bflo(p_.w), bfhi(o_.w) + sigmoidf_(g1[3]) * bfhi(p_.w));
;             *(u32x4*)(mixed + (size_t)(row0 + ai * HALF + m * 16) * 1024 + col0 + bj * HALF) = w;
;           }
	v_lshlrev_b32_e32 v78, 16, v118
	v_and_b32_e32 v79, 0xffff0000, v118
	v_lshlrev_b32_e32 v80, 16, v119
	v_and_b32_e32 v81, 0xffff0000, v119
	v_lshlrev_b32_e32 v74, 16, v120
	v_and_b32_e32 v75, 0xffff0000, v120
	v_lshlrev_b32_e32 v76, 16, v121
	v_and_b32_e32 v77, 0xffff0000, v121
	v_add_f32_e32 v146, 1.0, v146
	v_add_f32_e32 v147, 1.0, v147
	v_add_f32_e32 v148, 1.0, v148
	v_add_f32_e32 v149, 1.0, v149
	v_add_f32_e32 v150, 1.0, v150
	v_add_f32_e32 v151, 1.0, v151
	v_add_f32_e32 v152, 1.0, v152
	v_add_f32_e32 v153, 1.0, v153
	v_rcp_f32_e32 v146, v146
	v_rcp_f32_e32 v147, v147
	v_rcp_f32_e32 v148, v148
	v_rcp_f32_e32 v149, v149
	v_rcp_f32_e32 v150, v150
	v_rcp_f32_e32 v151, v151
	v_rcp_f32_e32 v152, v152
	v_rcp_f32_e32 v153, v153
	v_lshlrev_b32_e32 v154, 16, v114
	v_and_b32_e32 v155, 0xffff0000, v114
	v_lshlrev_b32_e32 v156, 16, v115
	v_and_b32_e32 v157, 0xffff0000, v115
	v_lshlrev_b32_e32 v158, 16, v116
	v_and_b32_e32 v159, 0xffff0000, v116
	v_lshlrev_b32_e32 v160, 16, v117
	v_and_b32_e32 v161, 0xffff0000, v117
	v_pk_fma_f32 v[146:147], v[146:147], v[78:79], v[154:155]
	v_pk_fma_f32 v[148:149], v[148:149], v[80:81], v[156:157]
	v_pk_fma_f32 v[150:151], v[150:151], v[74:75], v[158:159]
	v_pk_fma_f32 v[152:153], v[152:153], v[76:77], v[160:161]
	v_cvt_pk_bf16_f32 v162, v146, v147
	v_cvt_pk_bf16_f32 v163, v148, v149
	v_cvt_pk_bf16_f32 v164, v150, v151
	v_cvt_pk_bf16_f32 v165, v152, v153
	global_store_dwordx4 v212, v[162:165], s[100:101]
	global_load_dwordx4 v[94:97], v0, s[6:7]
	global_load_dwordx4 v[90:93], v212, s[98:99]
	s_add_u32 s6, s6, 0x2000
	s_addc_u32 s7, s7, 0
	v_fmamk_f32 v146, v70, 0xbfb8aa3b, v138
	v_fmamk_f32 v147, v71, 0xbfb8aa3b, v139
	v_fmamk_f32 v148, v72, 0xbfb8aa3b, v140
	v_fmamk_f32 v149, v73, 0xbfb8aa3b, v141
	v_fmamk_f32 v150, v66, 0xbfb8aa3b, v142
	v_fmamk_f32 v151, v67, 0xbfb8aa3b, v143
	v_fmamk_f32 v152, v68, 0xbfb8aa3b, v144
	v_fmamk_f32 v153, v69, 0xbfb8aa3b, v145
	v_exp_f32_e32 v146, v146
	v_exp_f32_e32 v147, v147
	v_exp_f32_e32 v148, v148
	v_exp_f32_e32 v149, v149
	v_exp_f32_e32 v150, v150
	v_exp_f32_e32 v151, v151
	v_exp_f32_e32 v152, v152
	v_exp_f32_e32 v153, v153
	s_waitcnt vmcnt(14)
	v_lshlrev_b32_e32 v70, 16, v184
	v_and_b32_e32 v71, 0xffff0000, v184
	v_lshlrev_b32_e32 v72, 16, v185
	v_and_b32_e32 v73, 0xffff0000, v185
	v_lshlrev_b32_e32 v66, 16, v186
	v_and_b32_e32 v67, 0xffff0000, v186
	v_lshlrev_b32_e32 v68, 16, v187
	v_and_b32_e32 v69, 0xffff0000, v187
	v_add_f32_e32 v146, 1.0, v146
	v_add_f32_e32 v147, 1.0, v147
	v_add_f32_e32 v148, 1.0, v148
	v_add_f32_e32 v149, 1.0, v149
	v_add_f32_e32 v150, 1.0, v150
	v_add_f32_e32 v151, 1.0, v151
	v_add_f32_e32 v152, 1.0, v152
	v_add_f32_e32 v153, 1.0, v153
	v_rcp_f32_e32 v146, v146
	v_rcp_f32_e32 v147, v147
	v_rcp_f32_e32 v148, v148
	v_rcp_f32_e32 v149, v149
	v_rcp_f32_e32 v150, v150
	v_rcp_f32_e32 v151, v151
	v_rcp_f32_e32 v152, v152
	v_rcp_f32_e32 v153, v153
	v_lshlrev_b32_e32 v154, 16, v188
	v_and_b32_e32 v155, 0xffff0000, v188
	v_lshlrev_b32_e32 v156, 16, v189
	v_and_b32_e32 v157, 0xffff0000, v189
	v_lshlrev_b32_e32 v158, 16, v190
	v_and_b32_e32 v159, 0xffff0000, v190
	v_lshlrev_b32_e32 v160, 16, v191
	v_and_b32_e32 v161, 0xffff0000, v191
	v_pk_fma_f32 v[146:147], v[146:147], v[70:71], v[154:155]
	v_pk_fma_f32 v[148:149], v[148:149], v[72:73], v[156:157]
	v_pk_fma_f32 v[150:151], v[150:151], v[66:67], v[158:159]
	v_pk_fma_f32 v[152:153], v[152:153], v[68:69], v[160:161]
	v_cvt_pk_bf16_f32 v162, v146, v147
	v_cvt_pk_bf16_f32 v163, v148, v149
	v_cvt_pk_bf16_f32 v164, v150, v151
	v_cvt_pk_bf16_f32 v165, v152, v153
	global_store_dwordx4 v212, v[162:165], s[100:101] offset:256
	s_add_u32 s100, s100, 0x28000
	s_addc_u32 s101, s101, 0
	global_load_dwordx4 v[122:125], v0, s[6:7]
	global_load_dwordx4 v[170:173], v212, s[98:99] offset:256
	s_add_u32 s6, s6, 0x2000
	s_addc_u32 s7, s7, 0
	s_add_u32 s98, s98, 0x8000
	s_addc_u32 s99, s99, 0
	v_fmamk_f32 v146, v62, 0xbfb8aa3b, v130
	v_fmamk_f32 v147, v63, 0xbfb8aa3b, v131
	v_fmamk_f32 v148, v64, 0xbfb8aa3b, v132
	v_fmamk_f32 v149, v65, 0xbfb8aa3b, v133
	v_fmamk_f32 v150, v58, 0xbfb8aa3b, v134
	v_fmamk_f32 v151, v59, 0xbfb8aa3b, v135
	v_fmamk_f32 v152, v60, 0xbfb8aa3b, v136
	v_fmamk_f32 v153, v61, 0xbfb8aa3b, v137
	v_exp_f32_e32 v146, v146
	v_exp_f32_e32 v147, v147
	v_exp_f32_e32 v148, v148
	v_exp_f32_e32 v149, v149
	v_exp_f32_e32 v150, v150
	v_exp_f32_e32 v151, v151
	v_exp_f32_e32 v152, v152
	v_exp_f32_e32 v153, v153
	s_waitcnt vmcnt(15)
	v_lshlrev_b32_e32 v62, 16, v110
	v_and_b32_e32 v63, 0xffff0000, v110
	v_lshlrev_b32_e32 v64, 16, v111
	v_and_b32_e32 v65, 0xffff0000, v111
	v_lshlrev_b32_e32 v58, 16, v112
	v_and_b32_e32 v59, 0xffff0000, v112
	v_lshlrev_b32_e32 v60, 16, v113
	v_and_b32_e32 v61, 0xffff0000, v113
	v_add_f32_e32 v146, 1.0, v146
	v_add_f32_e32 v147, 1.0, v147
	v_add_f32_e32 v148, 1.0, v148
	v_add_f32_e32 v149, 1.0, v149
	v_add_f32_e32 v150, 1.0, v150
	v_add_f32_e32 v151, 1.0, v151
	v_add_f32_e32 v152, 1.0, v152
	v_add_f32_e32 v153, 1.0, v153
	v_rcp_f32_e32 v146, v146
	v_rcp_f32_e32 v147, v147
	v_rcp_f32_e32 v148, v148
	v_rcp_f32_e32 v149, v149
	v_rcp_f32_e32 v150, v150
	v_rcp_f32_e32 v151, v151
	v_rcp_f32_e32 v152, v152
	v_rcp_f32_e32 v153, v153
	v_lshlrev_b32_e32 v154, 16, v106
	v_and_b32_e32 v155, 0xffff0000, v106
	v_lshlrev_b32_e32 v156, 16, v107
	v_and_b32_e32 v157, 0xffff0000, v107
	v_lshlrev_b32_e32 v158, 16, v108
	v_and_b32_e32 v159, 0xffff0000, v108
	v_lshlrev_b32_e32 v160, 16, v109
	v_and_b32_e32 v161, 0xffff0000, v109
	v_pk_fma_f32 v[146:147], v[146:147], v[62:63], v[154:155]
	v_pk_fma_f32 v[148:149], v[148:149], v[64:65], v[156:157]
	v_pk_fma_f32 v[150:151], v[150:151], v[58:59], v[158:159]
	v_pk_fma_f32 v[152:153], v[152:153], v[60:61], v[160:161]
	v_cvt_pk_bf16_f32 v162, v146, v147
	v_cvt_pk_bf16_f32 v163, v148, v149
	v_cvt_pk_bf16_f32 v164, v150, v151
	v_cvt_pk_bf16_f32 v165, v152, v153
	global_store_dwordx4 v212, v[162:165], s[100:101]
	global_load_dwordx4 v[86:89], v0, s[6:7]
	global_load_dwordx4 v[82:85], v212, s[98:99]
	s_add_u32 s6, s6, 0x2000
	s_addc_u32 s7, s7, 0
	v_fmamk_f32 v146, v54, 0xbfb8aa3b, v138
	v_fmamk_f32 v147, v55, 0xbfb8aa3b, v139
	v_fmamk_f32 v148, v56, 0xbfb8aa3b, v140
	v_fmamk_f32 v149, v57, 0xbfb8aa3b, v141
	v_fmamk_f32 v150, v50, 0xbfb8aa3b, v142
	v_fmamk_f32 v151, v51, 0xbfb8aa3b, v143
	v_fmamk_f32 v152, v52, 0xbfb8aa3b, v144
	v_fmamk_f32 v153, v53, 0xbfb8aa3b, v145
	v_exp_f32_e32 v146, v146
	v_exp_f32_e32 v147, v147
	v_exp_f32_e32 v148, v148
	v_exp_f32_e32 v149, v149
	v_exp_f32_e32 v150, v150
	v_exp_f32_e32 v151, v151
	v_exp_f32_e32 v152, v152
	v_exp_f32_e32 v153, v153
	s_waitcnt vmcnt(15)
; DI unsigned pack2(float a, float b) { fv2 v = {a, b}; return __builtin_bit_cast(unsigned, __builtin_convertvector(v, bfv2)); }
; DI float bflo(unsigned u) { return __uint_as_float(u << 16); }
; DI float bfhi(unsigned u) { return __uint_as_float(u & 0xffff0000u); }
; DI float sigmoidf_(float x) { return __builtin_amdgcn_rcpf(1.f + __expf(-x)); }
;   DI void operator()(const f32x4 (&acc)[2][2][4][2], const Unit& u, int wr, int wc, int fr, int fq) const {
;     ...
; #pragma unroll
;     for (int ai = 0; ai < 2; ++ai)
; #pragma unroll
;       for (int mp = 0; mp < 2; ++mp) {
;         u32x4 pv[2][2], ov[2][2];
;         f32x4 bv[2][2];
; #pragma unroll
;         for (int bj = 0; bj < 2; ++bj)
; #pragma unroll
;           for (int n = 0; n < 2; ++n) bv[bj][n] = *(const f32x4*)(bias + col0 + bj * HALF + 4 * n);
; #pragma unroll
;         for (int mm = 0; mm < 2; ++mm)
; #pragma unroll
;           for (int bj = 0; bj < 2; ++bj) {
;             const int m = mp * 2 + mm;
;             pv[mm][bj] = *(const u32x4*)(sb + (size_t)(((ai * 4 + m) * 2 + bj) * 8192) + toff);
;             ov[mm][bj] = (u32x4){0u, 0u, 0u, 0u};
;             if (!first) ov[mm][bj] = *(const u32x4*)(mixed + (size_t)(row0 + ai * HALF + m * 16) * 1024 + col0 + bj * HALF);
;           }
; #pragma unroll
;         for (int mm = 0; mm < 2; ++mm)
; #pragma unroll
;           for (int bj = 0; bj < 2; ++bj) {
;             const int m = mp * 2 + mm;
;             const f32x4 g0 = acc[ai][bj][m][0] + bv[bj][0], g1 = acc[ai][bj][m][1] + bv[bj][1];
;             const u32x4 p_ = pv[mm][bj], o_ = ov[mm][bj];
;             u32x4 w;
;             w.x = pack2(bflo(o_.x) + sigmoidf_(g0[0]) * bflo(p_.x), bfhi(o_.x) + sigmoidf_(g0[1]) * bfhi(p_.x));
;             w.y = pack2(bflo(o_.y) + sigmoidf_(g0[2]) * bflo(p_.y), bfhi(o_.y) + sigmoidf_(g0[3]) * bfhi(p_.y));
;             w.z = pack2(bflo(o_.z) + sigmoidf_(g1[0]) * bflo(p_.z), bfhi(o_.z) + sigmoidf_(g1[1]) * bfhi(p_.z));
;             w.w = pack2(bflo(o_.w) + sigmoidf_(g1[2]) * bflo(p_.w), bfhi(o_.w) + sigmoidf_(g1[3]) * bfhi(p_.w));
;             *(u32x4*)(mixed + (size_t)(row0 + ai * HALF + m * 16) * 1024 + col0 + bj * HALF) = w;
;           }
	v_lshlrev_b32_e32 v54, 16, v192
	v_and_b32_e32 v55, 0xffff0000, v192
	v_lshlrev_b32_e32 v56, 16, v193
	v_and_b32_e32 v57, 0xffff0000, v193
	v_lshlrev_b32_e32 v50, 16, v194
	v_and_b32_e32 v51, 0xffff0000, v194
	v_lshlrev_b32_e32 v52, 16, v195
	v_and_b32_e32 v53, 0xffff0000, v195
	v_add_f32_e32 v146, 1.0, v146
	v_add_f32_e32 v147, 1.0, v147
	v_add_f32_e32 v148, 1.0, v148
	v_add_f32_e32 v149, 1.0, v149
	v_add_f32_e32 v150, 1.0, v150
	v_add_f32_e32 v151, 1.0, v151
	v_add_f32_e32 v152, 1.0, v152
	v_add_f32_e32 v153, 1.0, v153
	v_rcp_f32_e32 v146, v146
	v_rcp_f32_e32 v147, v147
	v_rcp_f32_e32 v148, v148
	v_rcp_f32_e32 v149, v149
	v_rcp_f32_e32 v150, v150
	v_rcp_f32_e32 v151, v151
	v_rcp_f32_e32 v152, v152
	v_rcp_f32_e32 v153, v153
	v_lshlrev_b32_e32 v154, 16, v196
	v_and_b32_e32 v155, 0xffff0000, v196
	v_lshlrev_b32_e32 v156, 16, v197
	v_and_b32_e32 v157, 0xffff0000, v197
	v_lshlrev_b32_e32 v158, 16, v198
	v_and_b32_e32 v159, 0xffff0000, v198
	v_lshlrev_b32_e32 v160, 16, v199
	v_and_b32_e32 v161, 0xffff0000, v199
	v_pk_fma_f32 v[146:147], v[146:147], v[54:55], v[154:155]
	v_pk_fma_f32 v[148:149], v[148:149], v[56:57], v[156:157]
	v_pk_fma_f32 v[150:151], v[150:151], v[50:51], v[158:159]
	v_pk_fma_f32 v[152:153], v[152:153], v[52:53], v[160:161]
	v_cvt_pk_bf16_f32 v162, v146, v147
	v_cvt_pk_bf16_f32 v163, v148, v149
	v_cvt_pk_bf16_f32 v164, v150, v151
	v_cvt_pk_bf16_f32 v165, v152, v153
	global_store_dwordx4 v212, v[162:165], s[100:101] offset:256
	s_add_u32 s100, s100, 0x8000
	s_addc_u32 s101, s101, 0
	global_load_dwordx4 v[174:177], v0, s[6:7]
	global_load_dwordx4 v[118:121], v212, s[98:99] offset:256
	v_fmamk_f32 v146, v46, 0xbfb8aa3b, v130
	v_fmamk_f32 v147, v47, 0xbfb8aa3b, v131
	v_fmamk_f32 v148, v48, 0xbfb8aa3b, v132
	v_fmamk_f32 v149, v49, 0xbfb8aa3b, v133
	v_fmamk_f32 v150, v42, 0xbfb8aa3b, v134
	v_fmamk_f32 v151, v43, 0xbfb8aa3b, v135
	v_fmamk_f32 v152, v44, 0xbfb8aa3b, v136
	v_fmamk_f32 v153, v45, 0xbfb8aa3b, v137
	v_exp_f32_e32 v146, v146
	v_exp_f32_e32 v147, v147
	v_exp_f32_e32 v148, v148
	v_exp_f32_e32 v149, v149
	v_exp_f32_e32 v150, v150
	v_exp_f32_e32 v151, v151
	v_exp_f32_e32 v152, v152
	v_exp_f32_e32 v153, v153
	s_waitcnt vmcnt(15)
	v_lshlrev_b32_e32 v46, 16, v102
	v_and_b32_e32 v47, 0xffff0000, v102
	v_lshlrev_b32_e32 v48, 16, v103
	v_and_b32_e32 v49, 0xffff0000, v103
	v_lshlrev_b32_e32 v42, 16, v104
	v_and_b32_e32 v43, 0xffff0000, v104
	v_lshlrev_b32_e32 v44, 16, v105
	v_and_b32_e32 v45, 0xffff0000, v105
	v_add_f32_e32 v146, 1.0, v146
	v_add_f32_e32 v147, 1.0, v147
	v_add_f32_e32 v148, 1.0, v148
	v_add_f32_e32 v149, 1.0, v149
	v_add_f32_e32 v150, 1.0, v150
	v_add_f32_e32 v151, 1.0, v151
	v_add_f32_e32 v152, 1.0, v152
	v_add_f32_e32 v153, 1.0, v153
	v_rcp_f32_e32 v146, v146
	v_rcp_f32_e32 v147, v147
	v_rcp_f32_e32 v148, v148
	v_rcp_f32_e32 v149, v149
	v_rcp_f32_e32 v150, v150
	v_rcp_f32_e32 v151, v151
	v_rcp_f32_e32 v152, v152
	v_rcp_f32_e32 v153, v153
	v_lshlrev_b32_e32 v154, 16, v98
	v_and_b32_e32 v155, 0xffff0000, v98
	v_lshlrev_b32_e32 v156, 16, v99
	v_and_b32_e32 v157, 0xffff0000, v99
	v_lshlrev_b32_e32 v158, 16, v100
	v_and_b32_e32 v159, 0xffff0000, v100
	v_lshlrev_b32_e32 v160, 16, v101
	v_and_b32_e32 v161, 0xffff0000, v101
	v_pk_fma_f32 v[146:147], v[146:147], v[46:47], v[154:155]
	v_pk_fma_f32 v[148:149], v[148:149], v[48:49], v[156:157]
	v_pk_fma_f32 v[150:151], v[150:151], v[42:43], v[158:159]
	v_pk_fma_f32 v[152:153], v[152:153], v[44:45], v[160:161]
	v_cvt_pk_bf16_f32 v162, v146, v147
	v_cvt_pk_bf16_f32 v163, v148, v149
	v_cvt_pk_bf16_f32 v164, v150, v151
	v_cvt_pk_bf16_f32 v165, v152, v153
	global_store_dwordx4 v212, v[162:165], s[100:101]
	v_fmamk_f32 v146, v38, 0xbfb8aa3b, v138
	v_fmamk_f32 v147, v39, 0xbfb8aa3b, v139
	v_fmamk_f32 v148, v40, 0xbfb8aa3b, v140
	v_fmamk_f32 v149, v41, 0xbfb8aa3b, v141
	v_fmamk_f32 v150, v34, 0xbfb8aa3b, v142
	v_fmamk_f32 v151, v35, 0xbfb8aa3b, v143
	v_fmamk_f32 v152, v36, 0xbfb8aa3b, v144
	v_fmamk_f32 v153, v37, 0xbfb8aa3b, v145
	v_exp_f32_e32 v146, v146
	v_exp_f32_e32 v147, v147
	v_exp_f32_e32 v148, v148
	v_exp_f32_e32 v149, v149
	v_exp_f32_e32 v150, v150
	v_exp_f32_e32 v151, v151
	v_exp_f32_e32 v152, v152
	v_exp_f32_e32 v153, v153
	s_waitcnt vmcnt(13)
	v_lshlrev_b32_e32 v38, 16, v166
	v_and_b32_e32 v39, 0xffff0000, v166
	v_lshlrev_b32_e32 v40, 16, v167
	v_and_b32_e32 v41, 0xffff0000, v167
	v_lshlrev_b32_e32 v34, 16, v168
	v_and_b32_e32 v35, 0xffff0000, v168
	v_lshlrev_b32_e32 v36, 16, v169
	v_and_b32_e32 v37, 0xffff0000, v169
	v_add_f32_e32 v146, 1.0, v146
	v_add_f32_e32 v147, 1.0, v147
	v_add_f32_e32 v148, 1.0, v148
	v_add_f32_e32 v149, 1.0, v149
	v_add_f32_e32 v150, 1.0, v150
	v_add_f32_e32 v151, 1.0, v151
	v_add_f32_e32 v152, 1.0, v152
	v_add_f32_e32 v153, 1.0, v153
	v_rcp_f32_e32 v146, v146
	v_rcp_f32_e32 v147, v147
	v_rcp_f32_e32 v148, v148
	v_rcp_f32_e32 v149, v149
	v_rcp_f32_e32 v150, v150
	v_rcp_f32_e32 v151, v151
	v_rcp_f32_e32 v152, v152
	v_rcp_f32_e32 v153, v153
	v_lshlrev_b32_e32 v154, 16, v126
	v_and_b32_e32 v155, 0xffff0000, v126
	v_lshlrev_b32_e32 v156, 16, v127
	v_and_b32_e32 v157, 0xffff0000, v127
	v_lshlrev_b32_e32 v158, 16, v128
	v_and_b32_e32 v159, 0xffff0000, v128
	v_lshlrev_b32_e32 v160, 16, v129
	v_and_b32_e32 v161, 0xffff0000, v129
	v_pk_fma_f32 v[146:147], v[146:147], v[38:39], v[154:155]
	v_pk_fma_f32 v[148:149], v[148:149], v[40:41], v[156:157]
	v_pk_fma_f32 v[150:151], v[150:151], v[34:35], v[158:159]
	v_pk_fma_f32 v[152:153], v[152:153], v[36:37], v[160:161]
	v_cvt_pk_bf16_f32 v162, v146, v147
	v_cvt_pk_bf16_f32 v163, v148, v149
	v_cvt_pk_bf16_f32 v164, v150, v151
	v_cvt_pk_bf16_f32 v165, v152, v153
	global_store_dwordx4 v212, v[162:165], s[100:101] offset:256
	s_add_u32 s100, s100, 0x8000
	s_addc_u32 s101, s101, 0
	v_fmamk_f32 v146, v30, 0xbfb8aa3b, v130
	v_fmamk_f32 v147, v31, 0xbfb8aa3b, v131
	v_fmamk_f32 v148, v32, 0xbfb8aa3b, v132
	v_fmamk_f32 v149, v33, 0xbfb8aa3b, v133
	v_fmamk_f32 v150, v26, 0xbfb8aa3b, v134
	v_fmamk_f32 v151, v27, 0xbfb8aa3b, v135
	v_fmamk_f32 v152, v28, 0xbfb8aa3b, v136
	v_fmamk_f32 v153, v29, 0xbfb8aa3b, v137
	v_exp_f32_e32 v146, v146
	v_exp_f32_e32 v147, v147
	v_exp_f32_e32 v148, v148
	v_exp_f32_e32 v149, v149
	v_exp_f32_e32 v150, v150
	v_exp_f32_e32 v151, v151
	v_exp_f32_e32 v152, v152
	v_exp_f32_e32 v153, v153
	s_waitcnt vmcnt(11)
; DI unsigned pack2(float a, float b) { fv2 v = {a, b}; return __builtin_bit_cast(unsigned, __builtin_convertvector(v, bfv2)); }
; DI float bflo(unsigned u) { return __uint_as_float(u << 16); }
; DI float bfhi(unsigned u) { return __uint_as_float(u & 0xffff0000u); }
; DI float sigmoidf_(float x) { return __builtin_amdgcn_rcpf(1.f + __expf(-x)); }
;   DI void operator()(const f32x4 (&acc)[2][2][4][2], const Unit& u, int wr, int wc, int fr, int fq) const {
;     ...
; #pragma unroll
;     for (int ai = 0; ai < 2; ++ai)
; #pragma unroll
;       for (int mp = 0; mp < 2; ++mp) {
;         u32x4 pv[2][2], ov[2][2];
;         f32x4 bv[2][2];
; #pragma unroll
;         for (int bj = 0; bj < 2; ++bj)
; #pragma unroll
;           for (int n = 0; n < 2; ++n) bv[bj][n] = *(const f32x4*)(bias + col0 + bj * HALF + 4 * n);
; #pragma unroll
;         for (int mm = 0; mm < 2; ++mm)
; #pragma unroll
;           for (int bj = 0; bj < 2; ++bj) {
;             const int m = mp * 2 + mm;
;             pv[mm][bj] = *(const u32x4*)(sb + (size_t)(((ai * 4 + m) * 2 + bj) * 8192) + toff);
;             ov[mm][bj] = (u32x4){0u, 0u, 0u, 0u};
;             if (!first) ov[mm][bj] = *(const u32x4*)(mixed + (size_t)(row0 + ai * HALF + m * 16) * 1024 + col0 + bj * HALF);
;           }
; #pragma unroll
;         for (int mm = 0; mm < 2; ++mm)
; #pragma unroll
;           for (int bj = 0; bj < 2; ++bj) {
;             const int m = mp * 2 + mm;
;             const f32x4 g0 = acc[ai][bj][m][0] + bv[bj][0], g1 = acc[ai][bj][m][1] + bv[bj][1];
;             const u32x4 p_ = pv[mm][bj], o_ = ov[mm][bj];
;             u32x4 w;
;             w.x = pack2(bflo(o_.x) + sigmoidf_(g0[0]) * bflo(p_.x), bfhi(o_.x) + sigmoidf_(g0[1]) * bfhi(p_.x));
;             w.y = pack2(bflo(o_.y) + sigmoidf_(g0[2]) * bflo(p_.y), bfhi(o_.y) + sigmoidf_(g0[3]) * bfhi(p_.y));
;             w.z = pack2(bflo(o_.z) + sigmoidf_(g1[0]) * bflo(p_.z), bfhi(o_.z) + sigmoidf_(g1[1]) * bfhi(p_.z));
;             w.w = pack2(bflo(o_.w) + sigmoidf_(g1[2]) * bflo(p_.w), bfhi(o_.w) + sigmoidf_(g1[3]) * bfhi(p_.w));
;             *(u32x4*)(mixed + (size_t)(row0 + ai * HALF + m * 16) * 1024 + col0 + bj * HALF) = w;
;           }
	v_lshlrev_b32_e32 v30, 16, v94
	v_and_b32_e32 v31, 0xffff0000, v94
	v_lshlrev_b32_e32 v32, 16, v95
	v_and_b32_e32 v33, 0xffff0000, v95
	v_lshlrev_b32_e32 v26, 16, v96
	v_and_b32_e32 v27, 0xffff0000, v96
	v_lshlrev_b32_e32 v28, 16, v97
	v_and_b32_e32 v29, 0xffff0000, v97
	v_add_f32_e32 v146, 1.0, v146
	v_add_f32_e32 v147, 1.0, v147
	v_add_f32_e32 v148, 1.0, v148
	v_add_f32_e32 v149, 1.0, v149
	v_add_f32_e32 v150, 1.0, v150
	v_add_f32_e32 v151, 1.0, v151
	v_add_f32_e32 v152, 1.0, v152
	v_add_f32_e32 v153, 1.0, v153
	v_rcp_f32_e32 v146, v146
	v_rcp_f32_e32 v147, v147
	v_rcp_f32_e32 v148, v148
	v_rcp_f32_e32 v149, v149
	v_rcp_f32_e32 v150, v150
	v_rcp_f32_e32 v151, v151
	v_rcp_f32_e32 v152, v152
	v_rcp_f32_e32 v153, v153
	v_lshlrev_b32_e32 v154, 16, v90
	v_and_b32_e32 v155, 0xffff0000, v90
	v_lshlrev_b32_e32 v156, 16, v91
	v_and_b32_e32 v157, 0xffff0000, v91
	v_lshlrev_b32_e32 v158, 16, v92
	v_and_b32_e32 v159, 0xffff0000, v92
	v_lshlrev_b32_e32 v160, 16, v93
	v_and_b32_e32 v161, 0xffff0000, v93
	v_pk_fma_f32 v[146:147], v[146:147], v[30:31], v[154:155]
	v_pk_fma_f32 v[148:149], v[148:149], v[32:33], v[156:157]
	v_pk_fma_f32 v[150:151], v[150:151], v[26:27], v[158:159]
	v_pk_fma_f32 v[152:153], v[152:153], v[28:29], v[160:161]
	v_cvt_pk_bf16_f32 v162, v146, v147
	v_cvt_pk_bf16_f32 v163, v148, v149
	v_cvt_pk_bf16_f32 v164, v150, v151
	v_cvt_pk_bf16_f32 v165, v152, v153
	global_store_dwordx4 v212, v[162:165], s[100:101]
	v_fmamk_f32 v146, v22, 0xbfb8aa3b, v138
	v_fmamk_f32 v147, v23, 0xbfb8aa3b, v139
	v_fmamk_f32 v148, v24, 0xbfb8aa3b, v140
	v_fmamk_f32 v149, v25, 0xbfb8aa3b, v141
	v_fmamk_f32 v150, v18, 0xbfb8aa3b, v142
	v_fmamk_f32 v151, v19, 0xbfb8aa3b, v143
	v_fmamk_f32 v152, v20, 0xbfb8aa3b, v144
	v_fmamk_f32 v153, v21, 0xbfb8aa3b, v145
	v_exp_f32_e32 v146, v146
	v_exp_f32_e32 v147, v147
	v_exp_f32_e32 v148, v148
	v_exp_f32_e32 v149, v149
	v_exp_f32_e32 v150, v150
	v_exp_f32_e32 v151, v151
	v_exp_f32_e32 v152, v152
	v_exp_f32_e32 v153, v153
	s_waitcnt vmcnt(9)
	v_lshlrev_b32_e32 v22, 16, v122
	v_and_b32_e32 v23, 0xffff0000, v122
	v_lshlrev_b32_e32 v24, 16, v123
	v_and_b32_e32 v25, 0xffff0000, v123
	v_lshlrev_b32_e32 v18, 16, v124
	v_and_b32_e32 v19, 0xffff0000, v124
	v_lshlrev_b32_e32 v20, 16, v125
	v_and_b32_e32 v21, 0xffff0000, v125
	v_add_f32_e32 v146, 1.0, v146
	v_add_f32_e32 v147, 1.0, v147
	v_add_f32_e32 v148, 1.0, v148
	v_add_f32_e32 v149, 1.0, v149
	v_add_f32_e32 v150, 1.0, v150
	v_add_f32_e32 v151, 1.0, v151
	v_add_f32_e32 v152, 1.0, v152
	v_add_f32_e32 v153, 1.0, v153
	v_rcp_f32_e32 v146, v146
	v_rcp_f32_e32 v147, v147
	v_rcp_f32_e32 v148, v148
	v_rcp_f32_e32 v149, v149
	v_rcp_f32_e32 v150, v150
	v_rcp_f32_e32 v151, v151
	v_rcp_f32_e32 v152, v152
	v_rcp_f32_e32 v153, v153
	v_lshlrev_b32_e32 v154, 16, v170
	v_and_b32_e32 v155, 0xffff0000, v170
	v_lshlrev_b32_e32 v156, 16, v171
	v_and_b32_e32 v157, 0xffff0000, v171
	v_lshlrev_b32_e32 v158, 16, v172
	v_and_b32_e32 v159, 0xffff0000, v172
	v_lshlrev_b32_e32 v160, 16, v173
	v_and_b32_e32 v161, 0xffff0000, v173
	v_pk_fma_f32 v[146:147], v[146:147], v[22:23], v[154:155]
	v_pk_fma_f32 v[148:149], v[148:149], v[24:25], v[156:157]
	v_pk_fma_f32 v[150:151], v[150:151], v[18:19], v[158:159]
	v_pk_fma_f32 v[152:153], v[152:153], v[20:21], v[160:161]
	v_cvt_pk_bf16_f32 v162, v146, v147
	v_cvt_pk_bf16_f32 v163, v148, v149
	v_cvt_pk_bf16_f32 v164, v150, v151
	v_cvt_pk_bf16_f32 v165, v152, v153
	global_store_dwordx4 v212, v[162:165], s[100:101] offset:256
	s_add_u32 s100, s100, 0x8000
	s_addc_u32 s101, s101, 0
	v_fmamk_f32 v146, v14, 0xbfb8aa3b, v130
	v_fmamk_f32 v147, v15, 0xbfb8aa3b, v131
	v_fmamk_f32 v148, v16, 0xbfb8aa3b, v132
	v_fmamk_f32 v149, v17, 0xbfb8aa3b, v133
	v_fmamk_f32 v150, v10, 0xbfb8aa3b, v134
	v_fmamk_f32 v151, v11, 0xbfb8aa3b, v135
	v_fmamk_f32 v152, v12, 0xbfb8aa3b, v136
	v_fmamk_f32 v153, v13, 0xbfb8aa3b, v137
	v_exp_f32_e32 v146, v146
	v_exp_f32_e32 v147, v147
	v_exp_f32_e32 v148, v148
	v_exp_f32_e32 v149, v149
	v_exp_f32_e32 v150, v150
	v_exp_f32_e32 v151, v151
	v_exp_f32_e32 v152, v152
	v_exp_f32_e32 v153, v153
	s_waitcnt vmcnt(7)
	v_lshlrev_b32_e32 v14, 16, v86
	v_and_b32_e32 v15, 0xffff0000, v86
	v_lshlrev_b32_e32 v16, 16, v87
	v_and_b32_e32 v17, 0xffff0000, v87
	v_lshlrev_b32_e32 v10, 16, v88
	v_and_b32_e32 v11, 0xffff0000, v88
	v_lshlrev_b32_e32 v12, 16, v89
	v_and_b32_e32 v13, 0xffff0000, v89
	v_add_f32_e32 v146, 1.0, v146
	v_add_f32_e32 v147, 1.0, v147
	v_add_f32_e32 v148, 1.0, v148
	v_add_f32_e32 v149, 1.0, v149
	v_add_f32_e32 v150, 1.0, v150
	v_add_f32_e32 v151, 1.0, v151
	v_add_f32_e32 v152, 1.0, v152
	v_add_f32_e32 v153, 1.0, v153
	v_rcp_f32_e32 v146, v146
	v_rcp_f32_e32 v147, v147
	v_rcp_f32_e32 v148, v148
	v_rcp_f32_e32 v149, v149
	v_rcp_f32_e32 v150, v150
	v_rcp_f32_e32 v151, v151
	v_rcp_f32_e32 v152, v152
	v_rcp_f32_e32 v153, v153
	v_lshlrev_b32_e32 v154, 16, v82
	v_and_b32_e32 v155, 0xffff0000, v82
	v_lshlrev_b32_e32 v156, 16, v83
	v_and_b32_e32 v157, 0xffff0000, v83
	v_lshlrev_b32_e32 v158, 16, v84
	v_and_b32_e32 v159, 0xffff0000, v84
	v_lshlrev_b32_e32 v160, 16, v85
	v_and_b32_e32 v161, 0xffff0000, v85
	v_pk_fma_f32 v[146:147], v[146:147], v[14:15], v[154:155]
	v_pk_fma_f32 v[148:149], v[148:149], v[16:17], v[156:157]
	v_pk_fma_f32 v[150:151], v[150:151], v[10:11], v[158:159]
	v_pk_fma_f32 v[152:153], v[152:153], v[12:13], v[160:161]
	v_cvt_pk_bf16_f32 v162, v146, v147
	v_cvt_pk_bf16_f32 v163, v148, v149
	v_cvt_pk_bf16_f32 v164, v150, v151
	v_cvt_pk_bf16_f32 v165, v152, v153
	global_store_dwordx4 v212, v[162:165], s[100:101]
	v_fmamk_f32 v146, v6, 0xbfb8aa3b, v138
	v_fmamk_f32 v147, v7, 0xbfb8aa3b, v139
	v_fmamk_f32 v148, v8, 0xbfb8aa3b, v140
	v_fmamk_f32 v149, v9, 0xbfb8aa3b, v141
	v_fmamk_f32 v150, v2, 0xbfb8aa3b, v142
	v_fmamk_f32 v151, v3, 0xbfb8aa3b, v143
	v_fmamk_f32 v152, v4, 0xbfb8aa3b, v144
	v_fmamk_f32 v153, v5, 0xbfb8aa3b, v145
	v_exp_f32_e32 v146, v146
	v_exp_f32_e32 v147, v147
	v_exp_f32_e32 v148, v148
	v_exp_f32_e32 v149, v149
	v_exp_f32_e32 v150, v150
	v_exp_f32_e32 v151, v151
	v_exp_f32_e32 v152, v152
	v_exp_f32_e32 v153, v153
	s_waitcnt vmcnt(5)
; DI unsigned pack2(float a, float b) { fv2 v = {a, b}; return __builtin_bit_cast(unsigned, __builtin_convertvector(v, bfv2)); }
; DI float bflo(unsigned u) { return __uint_as_float(u << 16); }
; DI float bfhi(unsigned u) { return __uint_as_float(u & 0xffff0000u); }
; DI float sigmoidf_(float x) { return __builtin_amdgcn_rcpf(1.f + __expf(-x)); }
;   DI void operator()(const f32x4 (&acc)[2][2][4][2], const Unit& u, int wr, int wc, int fr, int fq) const {
;     ...
;           for (int n = 0; n < 2; ++n) bv[bj][n] = *(const f32x4*)(bias + col0 + bj * HALF + 4 * n);
; #pragma unroll
;         for (int mm = 0; mm < 2; ++mm)
; #pragma unroll
;           for (int bj = 0; bj < 2; ++bj) {
;             const int m = mp * 2 + mm;
;             pv[mm][bj] = *(const u32x4*)(sb + (size_t)(((ai * 4 + m) * 2 + bj) * 8192) + toff);
;             ov[mm][bj] = (u32x4){0u, 0u, 0u, 0u};
;             if (!first) ov[mm][bj] = *(const u32x4*)(mixed + (size_t)(row0 + ai * HALF + m * 16) * 1024 + col0 + bj * HALF);
;           }
; #pragma unroll
;         for (int mm = 0; mm < 2; ++mm)
; #pragma unroll
;           for (int bj = 0; bj < 2; ++bj) {
;             const int m = mp * 2 + mm;
;             const f32x4 g0 = acc[ai][bj][m][0] + bv[bj][0], g1 = acc[ai][bj][m][1] + bv[bj][1];
;             const u32x4 p_ = pv[mm][bj], o_ = ov[mm][bj];
;             u32x4 w;
;             w.x = pack2(bflo(o_.x) + sigmoidf_(g0[0]) * bflo(p_.x), bfhi(o_.x) + sigmoidf_(g0[1]) * bfhi(p_.x));
;             w.y = pack2(bflo(o_.y) + sigmoidf_(g0[2]) * bflo(p_.y), bfhi(o_.y) + sigmoidf_(g0[3]) * bfhi(p_.y));
;             w.z = pack2(bflo(o_.z) + sigmoidf_(g1[0]) * bflo(p_.z), bfhi(o_.z) + sigmoidf_(g1[1]) * bfhi(p_.z));
;             w.w = pack2(bflo(o_.w) + sigmoidf_(g1[2]) * bflo(p_.w), bfhi(o_.w) + sigmoidf_(g1[3]) * bfhi(p_.w));
;             *(u32x4*)(mixed + (size_t)(row0 + ai * HALF + m * 16) * 1024 + col0 + bj * HALF) = w;
;           }
	v_lshlrev_b32_e32 v6, 16, v174
	v_and_b32_e32 v7, 0xffff0000, v174
	v_lshlrev_b32_e32 v8, 16, v175
	v_and_b32_e32 v9, 0xffff0000, v175
	v_lshlrev_b32_e32 v2, 16, v176
	v_and_b32_e32 v3, 0xffff0000, v176
	v_lshlrev_b32_e32 v4, 16, v177
	v_and_b32_e32 v5, 0xffff0000, v177
	v_add_f32_e32 v146, 1.0, v146
	v_add_f32_e32 v147, 1.0, v147
	v_add_f32_e32 v148, 1.0, v148
	v_add_f32_e32 v149, 1.0, v149
	v_add_f32_e32 v150, 1.0, v150
	v_add_f32_e32 v151, 1.0, v151
	v_add_f32_e32 v152, 1.0, v152
	v_add_f32_e32 v153, 1.0, v153
	v_rcp_f32_e32 v146, v146
	v_rcp_f32_e32 v147, v147
	v_rcp_f32_e32 v148, v148
	v_rcp_f32_e32 v149, v149
	v_rcp_f32_e32 v150, v150
	v_rcp_f32_e32 v151, v151
	v_rcp_f32_e32 v152, v152
	v_rcp_f32_e32 v153, v153
	v_lshlrev_b32_e32 v154, 16, v118
	v_and_b32_e32 v155, 0xffff0000, v118
	v_lshlrev_b32_e32 v156, 16, v119
	v_and_b32_e32 v157, 0xffff0000, v119
	v_lshlrev_b32_e32 v158, 16, v120
	v_and_b32_e32 v159, 0xffff0000, v120
	v_lshlrev_b32_e32 v160, 16, v121
	v_and_b32_e32 v161, 0xffff0000, v121
	v_pk_fma_f32 v[146:147], v[146:147], v[6:7], v[154:155]
	v_pk_fma_f32 v[148:149], v[148:149], v[8:9], v[156:157]
	v_pk_fma_f32 v[150:151], v[150:151], v[2:3], v[158:159]
	v_pk_fma_f32 v[152:153], v[152:153], v[4:5], v[160:161]
	v_cvt_pk_bf16_f32 v162, v146, v147
	v_cvt_pk_bf16_f32 v163, v148, v149
	v_cvt_pk_bf16_f32 v164, v150, v151
	v_cvt_pk_bf16_f32 v165, v152, v153
	global_store_dwordx4 v212, v[162:165], s[100:101] offset:256
	s_branch .LBB0_930
.Lem_first:
	s_mov_b64 s[6:7], s[8:9]
	s_mov_b64 s[100:101], s[98:99]
	v_mov_b32_e32 v154, 0
	v_mov_b32_e32 v155, 0
	global_load_dwordx4 v[166:169], v0, s[6:7]
	s_add_u32 s6, s6, 0x2000
	s_addc_u32 s7, s7, 0
	global_load_dwordx4 v[170:173], v0, s[6:7]
	s_add_u32 s6, s6, 0x2000
	s_addc_u32 s7, s7, 0
	global_load_dwordx4 v[174:177], v0, s[6:7]
	s_add_u32 s6, s6, 0x2000
	s_addc_u32 s7, s7, 0
	global_load_dwordx4 v[184:187], v0, s[6:7]
	s_add_u32 s6, s6, 0x2000
	s_addc_u32 s7, s7, 0
	s_waitcnt vmcnt(4)
	v_mul_f32_e32 v130, 0xbfb8aa3b, v130
	v_mul_f32_e32 v131, 0xbfb8aa3b, v131
	v_mul_f32_e32 v132, 0xbfb8aa3b, v132
	v_mul_f32_e32 v133, 0xbfb8aa3b, v133
	v_mul_f32_e32 v134, 0xbfb8aa3b, v134
	v_mul_f32_e32 v135, 0xbfb8aa3b, v135
	v_mul_f32_e32 v136, 0xbfb8aa3b, v136
	v_mul_f32_e32 v137, 0xbfb8aa3b, v137
	v_mul_f32_e32 v138, 0xbfb8aa3b, v138
	v_mul_f32_e32 v139, 0xbfb8aa3b, v139
	v_mul_f32_e32 v140, 0xbfb8aa3b, v140
	v_mul_f32_e32 v141, 0xbfb8aa3b, v141
	v_mul_f32_e32 v142, 0xbfb8aa3b, v142
	v_mul_f32_e32 v143, 0xbfb8aa3b, v143
	v_mul_f32_e32 v144, 0xbfb8aa3b, v144
	v_mul_f32_e32 v145, 0xbfb8aa3b, v145
	v_fmamk_f32 v146, v126, 0xbfb8aa3b, v130
	v_fmamk_f32 v147, v127, 0xbfb8aa3b, v131
	v_fmamk_f32 v148, v128, 0xbfb8aa3b, v132
	v_fmamk_f32 v149, v129, 0xbfb8aa3b, v133
	v_fmamk_f32 v150, v122, 0xbfb8aa3b, v134
	v_fmamk_f32 v151, v123, 0xbfb8aa3b, v135
	v_fmamk_f32 v152, v124, 0xbfb8aa3b, v136
	v_fmamk_f32 v153, v125, 0xbfb8aa3b, v137
	v_exp_f32_e32 v146, v146
	v_exp_f32_e32 v147, v147
	v_exp_f32_e32 v148, v148
	v_exp_f32_e32 v149, v149
	v_exp_f32_e32 v150, v150
	v_exp_f32_e32 v151, v151
	v_exp_f32_e32 v152, v152
	v_exp_f32_e32 v153, v153
	s_waitcnt vmcnt(3)
	v_lshlrev_b32_e32 v126, 16, v166
	v_and_b32_e32 v127, 0xffff0000, v166
	v_lshlrev_b32_e32 v128, 16, v167
	v_and_b32_e32 v129, 0xffff0000, v167
	v_lshlrev_b32_e32 v122, 16, v168
	v_and_b32_e32 v123, 0xffff0000, v168
	v_lshlrev_b32_e32 v124, 16, v169
	v_and_b32_e32 v125, 0xffff0000, v169
	v_add_f32_e32 v146, 1.0, v146
	v_add_f32_e32 v147, 1.0, v147
	v_add_f32_e32 v148, 1.0, v148
	v_add_f32_e32 v149, 1.0, v149
	v_add_f32_e32 v150, 1.0, v150
	v_add_f32_e32 v151, 1.0, v151
	v_add_f32_e32 v152, 1.0, v152
	v_add_f32_e32 v153, 1.0, v153
	v_rcp_f32_e32 v146, v146
	v_rcp_f32_e32 v147, v147
	v_rcp_f32_e32 v148, v148
	v_rcp_f32_e32 v149, v149
	v_rcp_f32_e32 v150, v150
	v_rcp_f32_e32 v151, v151
	v_rcp_f32_e32 v152, v152
	v_rcp_f32_e32 v153, v153
	v_pk_fma_f32 v[146:147], v[146:147], v[126:127], v[154:155]
	v_pk_fma_f32 v[148:149], v[148:149], v[128:129], v[154:155]
	v_pk_fma_f32 v[150:151], v[150:151], v[122:123], v[154:155]
	v_pk_fma_f32 v[152:153], v[152:153], v[124:125], v[154:155]
	v_cvt_pk_bf16_f32 v162, v146, v147
	v_cvt_pk_bf16_f32 v163, v148, v149
	v_cvt_pk_bf16_f32 v164, v150, v151
	v_cvt_pk_bf16_f32 v165, v152, v153
	global_store_dwordx4 v212, v[162:165], s[100:101]
	global_load_dwordx4 v[188:191], v0, s[6:7]
	s_add_u32 s6, s6, 0x2000
	s_addc_u32 s7, s7, 0
	global_load_dwordx4 v[192:195], v0, s[6:7]
	s_add_u32 s6, s6, 0x2000
	s_addc_u32 s7, s7, 0
	global_load_dwordx4 v[196:199], v0, s[6:7]
	s_add_u32 s6, s6, 0x2000
	s_addc_u32 s7, s7, 0
	v_fmamk_f32 v146, v118, 0xbfb8aa3b, v138
	v_fmamk_f32 v147, v119, 0xbfb8aa3b, v139
	v_fmamk_f32 v148, v120, 0xbfb8aa3b, v140
	v_fmamk_f32 v149, v121, 0xbfb8aa3b, v141
	v_fmamk_f32 v150, v114, 0xbfb8aa3b, v142
	v_fmamk_f32 v151, v115, 0xbfb8aa3b, v143
	v_fmamk_f32 v152, v116, 0xbfb8aa3b, v144
	v_fmamk_f32 v153, v117, 0xbfb8aa3b, v145
	v_exp_f32_e32 v146, v146
	v_exp_f32_e32 v147, v147
	v_exp_f32_e32 v148, v148
	v_exp_f32_e32 v149, v149
	v_exp_f32_e32 v150, v150
	v_exp_f32_e32 v151, v151
	v_exp_f32_e32 v152, v152
	v_exp_f32_e32 v153, v153
	s_waitcnt vmcnt(6)
; DI unsigned pack2(float a, float b) { fv2 v = {a, b}; return __builtin_bit_cast(unsigned, __builtin_convertvector(v, bfv2)); }
; DI float bflo(unsigned u) { return __uint_as_float(u << 16); }
; DI float bfhi(unsigned u) { return __uint_as_float(u & 0xffff0000u); }
; DI float sigmoidf_(float x) { return __builtin_amdgcn_rcpf(1.f + __expf(-x)); }
;   DI void operator()(const f32x4 (&acc)[2][2][4][2], const Unit& u, int wr, int wc, int fr, int fq) const {
;     ...
; #pragma unroll
;         for (int mm = 0; mm < 2; ++mm)
; #pragma unroll
;           for (int bj = 0; bj < 2; ++bj) {
;             const int m = mp * 2 + mm;
;             const f32x4 g0 = acc[ai][bj][m][0] + bv[bj][0], g1 = acc[ai][bj][m][1] + bv[bj][1];
;             const u32x4 p_ = pv[mm][bj], o_ = ov[mm][bj];
;             u32x4 w;
;             w.x = pack2(bflo(o_.x) + sigmoidf_(g0[0]) * bflo(p_.x), bfhi(o_.x) + sigmoidf_(g0[1]) * bfhi(p_.x));
;             w.y = pack2(bflo(o_.y) + sigmoidf_(g0[2]) * bflo(p_.y), bfhi(o_.y) + sigmoidf_(g0[3]) * bfhi(p_.y));
;             w.z = pack2(bflo(o_.z) + sigmoidf_(g1[0]) * bflo(p_.z), bfhi(o_.z) + sigmoidf_(g1[1]) * bfhi(p_.z));
;             w.w = pack2(bflo(o_.w) + sigmoidf_(g1[2]) * bflo(p_.w), bfhi(o_.w) + sigmoidf_(g1[3]) * bfhi(p_.w));
;             *(u32x4*)(mixed + (size_t)(row0 + ai * HALF + m * 16) * 1024 + col0 + bj * HALF) = w;
;           }
	v_lshlrev_b32_e32 v118, 16, v170
	v_and_b32_e32 v119, 0xffff0000, v170
	v_lshlrev_b32_e32 v120, 16, v171
	v_and_b32_e32 v121, 0xffff0000, v171
	v_lshlrev_b32_e32 v114, 16, v172
	v_and_b32_e32 v115, 0xffff0000, v172
	v_lshlrev_b32_e32 v116, 16, v173
	v_and_b32_e32 v117, 0xffff0000, v173
	v_add_f32_e32 v146, 1.0, v146
	v_add_f32_e32 v147, 1.0, v147
	v_add_f32_e32 v148, 1.0, v148
	v_add_f32_e32 v149, 1.0, v149
	v_add_f32_e32 v150, 1.0, v150
	v_add_f32_e32 v151, 1.0, v151
	v_add_f32_e32 v152, 1.0, v152
	v_add_f32_e32 v153, 1.0, v153
	v_rcp_f32_e32 v146, v146
	v_rcp_f32_e32 v147, v147
	v_rcp_f32_e32 v148, v148
	v_rcp_f32_e32 v149, v149
	v_rcp_f32_e32 v150, v150
	v_rcp_f32_e32 v151, v151
	v_rcp_f32_e32 v152, v152
	v_rcp_f32_e32 v153, v153
	v_pk_fma_f32 v[146:147], v[146:147], v[118:119], v[154:155]
	v_pk_fma_f32 v[148:149], v[148:149], v[120:121], v[154:155]
	v_pk_fma_f32 v[150:151], v[150:151], v[114:115], v[154:155]
	v_pk_fma_f32 v[152:153], v[152:153], v[116:117], v[154:155]
	v_cvt_pk_bf16_f32 v162, v146, v147
	v_cvt_pk_bf16_f32 v163, v148, v149
	v_cvt_pk_bf16_f32 v164, v150, v151
	v_cvt_pk_bf16_f32 v165, v152, v153
	global_store_dwordx4 v212, v[162:165], s[100:101] offset:256
	s_add_u32 s100, s100, 0x8000
	s_addc_u32 s101, s101, 0
	global_load_dwordx4 v[166:169], v0, s[6:7]
	s_add_u32 s6, s6, 0x2000
	s_addc_u32 s7, s7, 0
	v_fmamk_f32 v146, v110, 0xbfb8aa3b, v130
	v_fmamk_f32 v147, v111, 0xbfb8aa3b, v131
	v_fmamk_f32 v148, v112, 0xbfb8aa3b, v132
	v_fmamk_f32 v149, v113, 0xbfb8aa3b, v133
	v_fmamk_f32 v150, v106, 0xbfb8aa3b, v134
	v_fmamk_f32 v151, v107, 0xbfb8aa3b, v135
	v_fmamk_f32 v152, v108, 0xbfb8aa3b, v136
	v_fmamk_f32 v153, v109, 0xbfb8aa3b, v137
	v_exp_f32_e32 v146, v146
	v_exp_f32_e32 v147, v147
	v_exp_f32_e32 v148, v148
	v_exp_f32_e32 v149, v149
	v_exp_f32_e32 v150, v150
	v_exp_f32_e32 v151, v151
	v_exp_f32_e32 v152, v152
	v_exp_f32_e32 v153, v153
	s_waitcnt vmcnt(7)
	v_lshlrev_b32_e32 v110, 16, v174
	v_and_b32_e32 v111, 0xffff0000, v174
	v_lshlrev_b32_e32 v112, 16, v175
	v_and_b32_e32 v113, 0xffff0000, v175
	v_lshlrev_b32_e32 v106, 16, v176
	v_and_b32_e32 v107, 0xffff0000, v176
	v_lshlrev_b32_e32 v108, 16, v177
	v_and_b32_e32 v109, 0xffff0000, v177
	v_add_f32_e32 v146, 1.0, v146
	v_add_f32_e32 v147, 1.0, v147
	v_add_f32_e32 v148, 1.0, v148
	v_add_f32_e32 v149, 1.0, v149
	v_add_f32_e32 v150, 1.0, v150
	v_add_f32_e32 v151, 1.0, v151
	v_add_f32_e32 v152, 1.0, v152
	v_add_f32_e32 v153, 1.0, v153
	v_rcp_f32_e32 v146, v146
	v_rcp_f32_e32 v147, v147
	v_rcp_f32_e32 v148, v148
	v_rcp_f32_e32 v149, v149
	v_rcp_f32_e32 v150, v150
	v_rcp_f32_e32 v151, v151
	v_rcp_f32_e32 v152, v152
	v_rcp_f32_e32 v153, v153
	v_pk_fma_f32 v[146:147], v[146:147], v[110:111], v[154:155]
	v_pk_fma_f32 v[148:149], v[148:149], v[112:113], v[154:155]
	v_pk_fma_f32 v[150:151], v[150:151], v[106:107], v[154:155]
	v_pk_fma_f32 v[152:153], v[152:153], v[108:109], v[154:155]
	v_cvt_pk_bf16_f32 v162, v146, v147
	v_cvt_pk_bf16_f32 v163, v148, v149
	v_cvt_pk_bf16_f32 v164, v150, v151
	v_cvt_pk_bf16_f32 v165, v152, v153
	global_store_dwordx4 v212, v[162:165], s[100:101]
	global_load_dwordx4 v[126:129], v0, s[6:7]
	s_add_u32 s6, s6, 0x2000
	s_addc_u32 s7, s7, 0
	v_fmamk_f32 v146, v102, 0xbfb8aa3b, v138
	v_fmamk_f32 v147, v103, 0xbfb8aa3b, v139
	v_fmamk_f32 v148, v104, 0xbfb8aa3b, v140
	v_fmamk_f32 v149, v105, 0xbfb8aa3b, v141
	v_fmamk_f32 v150, v98, 0xbfb8aa3b, v142
	v_fmamk_f32 v151, v99, 0xbfb8aa3b, v143
	v_fmamk_f32 v152, v100, 0xbfb8aa3b, v144
	v_fmamk_f32 v153, v101, 0xbfb8aa3b, v145
	v_exp_f32_e32 v146, v146
	v_exp_f32_e32 v147, v147
	v_exp_f32_e32 v148, v148
	v_exp_f32_e32 v149, v149
	v_exp_f32_e32 v150, v150
	v_exp_f32_e32 v151, v151
	v_exp_f32_e32 v152, v152
	v_exp_f32_e32 v153, v153
	s_waitcnt vmcnt(8)
	v_lshlrev_b32_e32 v102, 16, v184
	v_and_b32_e32 v103, 0xffff0000, v184
	v_lshlrev_b32_e32 v104, 16, v185
	v_and_b32_e32 v105, 0xffff0000, v185
	v_lshlrev_b32_e32 v98, 16, v186
	v_and_b32_e32 v99, 0xffff0000, v186
	v_lshlrev_b32_e32 v100, 16, v187
	v_and_b32_e32 v101, 0xffff0000, v187
	v_add_f32_e32 v146, 1.0, v146
	v_add_f32_e32 v147, 1.0, v147
	v_add_f32_e32 v148, 1.0, v148
	v_add_f32_e32 v149, 1.0, v149
	v_add_f32_e32 v150, 1.0, v150
	v_add_f32_e32 v151, 1.0, v151
	v_add_f32_e32 v152, 1.0, v152
	v_add_f32_e32 v153, 1.0, v153
	v_rcp_f32_e32 v146, v146
	v_rcp_f32_e32 v147, v147
	v_rcp_f32_e32 v148, v148
	v_rcp_f32_e32 v149, v149
	v_rcp_f32_e32 v150, v150
	v_rcp_f32_e32 v151, v151
	v_rcp_f32_e32 v152, v152
	v_rcp_f32_e32 v153, v153
	v_pk_fma_f32 v[146:147], v[146:147], v[102:103], v[154:155]
	v_pk_fma_f32 v[148:149], v[148:149], v[104:105], v[154:155]
	v_pk_fma_f32 v[150:151], v[150:151], v[98:99], v[154:155]
	v_pk_fma_f32 v[152:153], v[152:153], v[100:101], v[154:155]
	v_cvt_pk_bf16_f32 v162, v146, v147
	v_cvt_pk_bf16_f32 v163, v148, v149
	v_cvt_pk_bf16_f32 v164, v150, v151
	v_cvt_pk_bf16_f32 v165, v152, v153
	global_store_dwordx4 v212, v[162:165], s[100:101] offset:256
	s_add_u32 s100, s100, 0x8000
	s_addc_u32 s101, s101, 0
	global_load_dwordx4 v[122:125], v0, s[6:7]
	s_add_u32 s6, s6, 0x2000
	s_addc_u32 s7, s7, 0
	v_fmamk_f32 v146, v94, 0xbfb8aa3b, v130
	v_fmamk_f32 v147, v95, 0xbfb8aa3b, v131
	v_fmamk_f32 v148, v96, 0xbfb8aa3b, v132
	v_fmamk_f32 v149, v97, 0xbfb8aa3b, v133
	v_fmamk_f32 v150, v90, 0xbfb8aa3b, v134
	v_fmamk_f32 v151, v91, 0xbfb8aa3b, v135
	v_fmamk_f32 v152, v92, 0xbfb8aa3b, v136
	v_fmamk_f32 v153, v93, 0xbfb8aa3b, v137
	v_exp_f32_e32 v146, v146
	v_exp_f32_e32 v147, v147
	v_exp_f32_e32 v148, v148
	v_exp_f32_e32 v149, v149
	v_exp_f32_e32 v150, v150
	v_exp_f32_e32 v151, v151
	v_exp_f32_e32 v152, v152
	v_exp_f32_e32 v153, v153
	s_waitcnt vmcnt(8)
; DI unsigned pack2(float a, float b) { fv2 v = {a, b}; return __builtin_bit_cast(unsigned, __builtin_convertvector(v, bfv2)); }
; DI float bflo(unsigned u) { return __uint_as_float(u << 16); }
; DI float bfhi(unsigned u) { return __uint_as_float(u & 0xffff0000u); }
; DI float sigmoidf_(float x) { return __builtin_amdgcn_rcpf(1.f + __expf(-x)); }
;   DI void operator()(const f32x4 (&acc)[2][2][4][2], const Unit& u, int wr, int wc, int fr, int fq) const {
;     ...
; #pragma unroll
;         for (int mm = 0; mm < 2; ++mm)
; #pragma unroll
;           for (int bj = 0; bj < 2; ++bj) {
;             const int m = mp * 2 + mm;
;             const f32x4 g0 = acc[ai][bj][m][0] + bv[bj][0], g1 = acc[ai][bj][m][1] + bv[bj][1];
;             const u32x4 p_ = pv[mm][bj], o_ = ov[mm][bj];
;             u32x4 w;
;             w.x = pack2(bflo(o_.x) + sigmoidf_(g0[0]) * bflo(p_.x), bfhi(o_.x) + sigmoidf_(g0[1]) * bfhi(p_.x));
;             w.y = pack2(bflo(o_.y) + sigmoidf_(g0[2]) * bflo(p_.y), bfhi(o_.y) + sigmoidf_(g0[3]) * bfhi(p_.y));
;             w.z = pack2(bflo(o_.z) + sigmoidf_(g1[0]) * bflo(p_.z), bfhi(o_.z) + sigmoidf_(g1[1]) * bfhi(p_.z));
;             w.w = pack2(bflo(o_.w) + sigmoidf_(g1[2]) * bflo(p_.w), bfhi(o_.w) + sigmoidf_(g1[3]) * bfhi(p_.w));
;             *(u32x4*)(mixed + (size_t)(row0 + ai * HALF + m * 16) * 1024 + col0 + bj * HALF) = w;
;           }
	v_lshlrev_b32_e32 v94, 16, v188
	v_and_b32_e32 v95, 0xffff0000, v188
	v_lshlrev_b32_e32 v96, 16, v189
	v_and_b32_e32 v97, 0xffff0000, v189
	v_lshlrev_b32_e32 v90, 16, v190
	v_and_b32_e32 v91, 0xffff0000, v190
	v_lshlrev_b32_e32 v92, 16, v191
	v_and_b32_e32 v93, 0xffff0000, v191
	v_add_f32_e32 v146, 1.0, v146
	v_add_f32_e32 v147, 1.0, v147
	v_add_f32_e32 v148, 1.0, v148
	v_add_f32_e32 v149, 1.0, v149
	v_add_f32_e32 v150, 1.0, v150
	v_add_f32_e32 v151, 1.0, v151
	v_add_f32_e32 v152, 1.0, v152
	v_add_f32_e32 v153, 1.0, v153
	v_rcp_f32_e32 v146, v146
	v_rcp_f32_e32 v147, v147
	v_rcp_f32_e32 v148, v148
	v_rcp_f32_e32 v149, v149
	v_rcp_f32_e32 v150, v150
	v_rcp_f32_e32 v151, v151
	v_rcp_f32_e32 v152, v152
	v_rcp_f32_e32 v153, v153
	v_pk_fma_f32 v[146:147], v[146:147], v[94:95], v[154:155]
	v_pk_fma_f32 v[148:149], v[148:149], v[96:97], v[154:155]
	v_pk_fma_f32 v[150:151], v[150:151], v[90:91], v[154:155]
	v_pk_fma_f32 v[152:153], v[152:153], v[92:93], v[154:155]
	v_cvt_pk_bf16_f32 v162, v146, v147
	v_cvt_pk_bf16_f32 v163, v148, v149
	v_cvt_pk_bf16_f32 v164, v150, v151
	v_cvt_pk_bf16_f32 v165, v152, v153
	global_store_dwordx4 v212, v[162:165], s[100:101]
	global_load_dwordx4 v[170:173], v0, s[6:7]
	s_add_u32 s6, s6, 0x2000
	s_addc_u32 s7, s7, 0
	v_fmamk_f32 v146, v86, 0xbfb8aa3b, v138
	v_fmamk_f32 v147, v87, 0xbfb8aa3b, v139
	v_fmamk_f32 v148, v88, 0xbfb8aa3b, v140
	v_fmamk_f32 v149, v89, 0xbfb8aa3b, v141
	v_fmamk_f32 v150, v82, 0xbfb8aa3b, v142
	v_fmamk_f32 v151, v83, 0xbfb8aa3b, v143
	v_fmamk_f32 v152, v84, 0xbfb8aa3b, v144
	v_fmamk_f32 v153, v85, 0xbfb8aa3b, v145
	v_exp_f32_e32 v146, v146
	v_exp_f32_e32 v147, v147
	v_exp_f32_e32 v148, v148
	v_exp_f32_e32 v149, v149
	v_exp_f32_e32 v150, v150
	v_exp_f32_e32 v151, v151
	v_exp_f32_e32 v152, v152
	v_exp_f32_e32 v153, v153
	s_waitcnt vmcnt(9)
	v_lshlrev_b32_e32 v86, 16, v192
	v_and_b32_e32 v87, 0xffff0000, v192
	v_lshlrev_b32_e32 v88, 16, v193
	v_and_b32_e32 v89, 0xffff0000, v193
	v_lshlrev_b32_e32 v82, 16, v194
	v_and_b32_e32 v83, 0xffff0000, v194
	v_lshlrev_b32_e32 v84, 16, v195
	v_and_b32_e32 v85, 0xffff0000, v195
	v_add_f32_e32 v146, 1.0, v146
	v_add_f32_e32 v147, 1.0, v147
	v_add_f32_e32 v148, 1.0, v148
	v_add_f32_e32 v149, 1.0, v149
	v_add_f32_e32 v150, 1.0, v150
	v_add_f32_e32 v151, 1.0, v151
	v_add_f32_e32 v152, 1.0, v152
	v_add_f32_e32 v153, 1.0, v153
	v_rcp_f32_e32 v146, v146
	v_rcp_f32_e32 v147, v147
	v_rcp_f32_e32 v148, v148
	v_rcp_f32_e32 v149, v149
	v_rcp_f32_e32 v150, v150
	v_rcp_f32_e32 v151, v151
	v_rcp_f32_e32 v152, v152
	v_rcp_f32_e32 v153, v153
	v_pk_fma_f32 v[146:147], v[146:147], v[86:87], v[154:155]
	v_pk_fma_f32 v[148:149], v[148:149], v[88:89], v[154:155]
	v_pk_fma_f32 v[150:151], v[150:151], v[82:83], v[154:155]
	v_pk_fma_f32 v[152:153], v[152:153], v[84:85], v[154:155]
	v_cvt_pk_bf16_f32 v162, v146, v147
	v_cvt_pk_bf16_f32 v163, v148, v149
	v_cvt_pk_bf16_f32 v164, v150, v151
	v_cvt_pk_bf16_f32 v165, v152, v153
	global_store_dwordx4 v212, v[162:165], s[100:101] offset:256
	s_add_u32 s100, s100, 0x8000
	s_addc_u32 s101, s101, 0
	global_load_dwordx4 v[118:121], v0, s[6:7]
	s_add_u32 s6, s6, 0x2000
	s_addc_u32 s7, s7, 0
	v_fmamk_f32 v146, v78, 0xbfb8aa3b, v130
	v_fmamk_f32 v147, v79, 0xbfb8aa3b, v131
	v_fmamk_f32 v148, v80, 0xbfb8aa3b, v132
	v_fmamk_f32 v149, v81, 0xbfb8aa3b, v133
	v_fmamk_f32 v150, v74, 0xbfb8aa3b, v134
	v_fmamk_f32 v151, v75, 0xbfb8aa3b, v135
	v_fmamk_f32 v152, v76, 0xbfb8aa3b, v136
	v_fmamk_f32 v153, v77, 0xbfb8aa3b, v137
	v_exp_f32_e32 v146, v146
	v_exp_f32_e32 v147, v147
	v_exp_f32_e32 v148, v148
	v_exp_f32_e32 v149, v149
	v_exp_f32_e32 v150, v150
	v_exp_f32_e32 v151, v151
	v_exp_f32_e32 v152, v152
	v_exp_f32_e32 v153, v153
	s_waitcnt vmcnt(10)
	v_lshlrev_b32_e32 v78, 16, v196
	v_and_b32_e32 v79, 0xffff0000, v196
	v_lshlrev_b32_e32 v80, 16, v197
	v_and_b32_e32 v81, 0xffff0000, v197
	v_lshlrev_b32_e32 v74, 16, v198
	v_and_b32_e32 v75, 0xffff0000, v198
	v_lshlrev_b32_e32 v76, 16, v199
	v_and_b32_e32 v77, 0xffff0000, v199
	v_add_f32_e32 v146, 1.0, v146
	v_add_f32_e32 v147, 1.0, v147
	v_add_f32_e32 v148, 1.0, v148
	v_add_f32_e32 v149, 1.0, v149
	v_add_f32_e32 v150, 1.0, v150
	v_add_f32_e32 v151, 1.0, v151
	v_add_f32_e32 v152, 1.0, v152
	v_add_f32_e32 v153, 1.0, v153
	v_rcp_f32_e32 v146, v146
	v_rcp_f32_e32 v147, v147
	v_rcp_f32_e32 v148, v148
	v_rcp_f32_e32 v149, v149
	v_rcp_f32_e32 v150, v150
	v_rcp_f32_e32 v151, v151
	v_rcp_f32_e32 v152, v152
	v_rcp_f32_e32 v153, v153
	v_pk_fma_f32 v[146:147], v[146:147], v[78:79], v[154:155]
	v_pk_fma_f32 v[148:149], v[148:149], v[80:81], v[154:155]
	v_pk_fma_f32 v[150:151], v[150:151], v[74:75], v[154:155]
	v_pk_fma_f32 v[152:153], v[152:153], v[76:77], v[154:155]
	v_cvt_pk_bf16_f32 v162, v146, v147
	v_cvt_pk_bf16_f32 v163, v148, v149
	v_cvt_pk_bf16_f32 v164, v150, v151
	v_cvt_pk_bf16_f32 v165, v152, v153
	global_store_dwordx4 v212, v[162:165], s[100:101]
	global_load_dwordx4 v[114:117], v0, s[6:7]
	s_add_u32 s6, s6, 0x2000
	s_addc_u32 s7, s7, 0
	v_fmamk_f32 v146, v70, 0xbfb8aa3b, v138
	v_fmamk_f32 v147, v71, 0xbfb8aa3b, v139
	v_fmamk_f32 v148, v72, 0xbfb8aa3b, v140
	v_fmamk_f32 v149, v73, 0xbfb8aa3b, v141
	v_fmamk_f32 v150, v66, 0xbfb8aa3b, v142
	v_fmamk_f32 v151, v67, 0xbfb8aa3b, v143
	v_fmamk_f32 v152, v68, 0xbfb8aa3b, v144
	v_fmamk_f32 v153, v69, 0xbfb8aa3b, v145
	v_exp_f32_e32 v146, v146
	v_exp_f32_e32 v147, v147
	v_exp_f32_e32 v148, v148
	v_exp_f32_e32 v149, v149
	v_exp_f32_e32 v150, v150
	v_exp_f32_e32 v151, v151
	v_exp_f32_e32 v152, v152
	v_exp_f32_e32 v153, v153
	s_waitcnt vmcnt(10)
; DI unsigned pack2(float a, float b) { fv2 v = {a, b}; return __builtin_bit_cast(unsigned, __builtin_convertvector(v, bfv2)); }
; DI float bflo(unsigned u) { return __uint_as_float(u << 16); }
; DI float bfhi(unsigned u) { return __uint_as_float(u & 0xffff0000u); }
; DI float sigmoidf_(float x) { return __builtin_amdgcn_rcpf(1.f + __expf(-x)); }
;   DI void operator()(const f32x4 (&acc)[2][2][4][2], const Unit& u, int wr, int wc, int fr, int fq) const {
;     ...
; #pragma unroll
;         for (int mm = 0; mm < 2; ++mm)
; #pragma unroll
;           for (int bj = 0; bj < 2; ++bj) {
;             const int m = mp * 2 + mm;
;             const f32x4 g0 = acc[ai][bj][m][0] + bv[bj][0], g1 = acc[ai][bj][m][1] + bv[bj][1];
;             const u32x4 p_ = pv[mm][bj], o_ = ov[mm][bj];
;             u32x4 w;
;             w.x = pack2(bflo(o_.x) + sigmoidf_(g0[0]) * bflo(p_.x), bfhi(o_.x) + sigmoidf_(g0[1]) * bfhi(p_.x));
;             w.y = pack2(bflo(o_.y) + sigmoidf_(g0[2]) * bflo(p_.y), bfhi(o_.y) + sigmoidf_(g0[3]) * bfhi(p_.y));
;             w.z = pack2(bflo(o_.z) + sigmoidf_(g1[0]) * bflo(p_.z), bfhi(o_.z) + sigmoidf_(g1[1]) * bfhi(p_.z));
;             w.w = pack2(bflo(o_.w) + sigmoidf_(g1[2]) * bflo(p_.w), bfhi(o_.w) + sigmoidf_(g1[3]) * bfhi(p_.w));
;             *(u32x4*)(mixed + (size_t)(row0 + ai * HALF + m * 16) * 1024 + col0 + bj * HALF) = w;
;           }
	v_lshlrev_b32_e32 v70, 16, v166
	v_and_b32_e32 v71, 0xffff0000, v166
	v_lshlrev_b32_e32 v72, 16, v167
	v_and_b32_e32 v73, 0xffff0000, v167
	v_lshlrev_b32_e32 v66, 16, v168
	v_and_b32_e32 v67, 0xffff0000, v168
	v_lshlrev_b32_e32 v68, 16, v169
	v_and_b32_e32 v69, 0xffff0000, v169
	v_add_f32_e32 v146, 1.0, v146
	v_add_f32_e32 v147, 1.0, v147
	v_add_f32_e32 v148, 1.0, v148
	v_add_f32_e32 v149, 1.0, v149
	v_add_f32_e32 v150, 1.0, v150
	v_add_f32_e32 v151, 1.0, v151
	v_add_f32_e32 v152, 1.0, v152
	v_add_f32_e32 v153, 1.0, v153
	v_rcp_f32_e32 v146, v146
	v_rcp_f32_e32 v147, v147
	v_rcp_f32_e32 v148, v148
	v_rcp_f32_e32 v149, v149
	v_rcp_f32_e32 v150, v150
	v_rcp_f32_e32 v151, v151
	v_rcp_f32_e32 v152, v152
	v_rcp_f32_e32 v153, v153
	v_pk_fma_f32 v[146:147], v[146:147], v[70:71], v[154:155]
	v_pk_fma_f32 v[148:149], v[148:149], v[72:73], v[154:155]
	v_pk_fma_f32 v[150:151], v[150:151], v[66:67], v[154:155]
	v_pk_fma_f32 v[152:153], v[152:153], v[68:69], v[154:155]
	v_cvt_pk_bf16_f32 v162, v146, v147
	v_cvt_pk_bf16_f32 v163, v148, v149
	v_cvt_pk_bf16_f32 v164, v150, v151
	v_cvt_pk_bf16_f32 v165, v152, v153
	global_store_dwordx4 v212, v[162:165], s[100:101] offset:256
	s_add_u32 s100, s100, 0x28000
	s_addc_u32 s101, s101, 0
	global_load_dwordx4 v[174:177], v0, s[6:7]
	s_add_u32 s6, s6, 0x2000
	s_addc_u32 s7, s7, 0
	v_fmamk_f32 v146, v62, 0xbfb8aa3b, v130
	v_fmamk_f32 v147, v63, 0xbfb8aa3b, v131
	v_fmamk_f32 v148, v64, 0xbfb8aa3b, v132
	v_fmamk_f32 v149, v65, 0xbfb8aa3b, v133
	v_fmamk_f32 v150, v58, 0xbfb8aa3b, v134
	v_fmamk_f32 v151, v59, 0xbfb8aa3b, v135
	v_fmamk_f32 v152, v60, 0xbfb8aa3b, v136
	v_fmamk_f32 v153, v61, 0xbfb8aa3b, v137
	v_exp_f32_e32 v146, v146
	v_exp_f32_e32 v147, v147
	v_exp_f32_e32 v148, v148
	v_exp_f32_e32 v149, v149
	v_exp_f32_e32 v150, v150
	v_exp_f32_e32 v151, v151
	v_exp_f32_e32 v152, v152
	v_exp_f32_e32 v153, v153
	s_waitcnt vmcnt(10)
	v_lshlrev_b32_e32 v62, 16, v126
	v_and_b32_e32 v63, 0xffff0000, v126
	v_lshlrev_b32_e32 v64, 16, v127
	v_and_b32_e32 v65, 0xffff0000, v127
	v_lshlrev_b32_e32 v58, 16, v128
	v_and_b32_e32 v59, 0xffff0000, v128
	v_lshlrev_b32_e32 v60, 16, v129
	v_and_b32_e32 v61, 0xffff0000, v129
	v_add_f32_e32 v146, 1.0, v146
	v_add_f32_e32 v147, 1.0, v147
	v_add_f32_e32 v148, 1.0, v148
	v_add_f32_e32 v149, 1.0, v149
	v_add_f32_e32 v150, 1.0, v150
	v_add_f32_e32 v151, 1.0, v151
	v_add_f32_e32 v152, 1.0, v152
	v_add_f32_e32 v153, 1.0, v153
	v_rcp_f32_e32 v146, v146
	v_rcp_f32_e32 v147, v147
	v_rcp_f32_e32 v148, v148
	v_rcp_f32_e32 v149, v149
	v_rcp_f32_e32 v150, v150
	v_rcp_f32_e32 v151, v151
	v_rcp_f32_e32 v152, v152
	v_rcp_f32_e32 v153, v153
	v_pk_fma_f32 v[146:147], v[146:147], v[62:63], v[154:155]
	v_pk_fma_f32 v[148:149], v[148:149], v[64:65], v[154:155]
	v_pk_fma_f32 v[150:151], v[150:151], v[58:59], v[154:155]
	v_pk_fma_f32 v[152:153], v[152:153], v[60:61], v[154:155]
	v_cvt_pk_bf16_f32 v162, v146, v147
	v_cvt_pk_bf16_f32 v163, v148, v149
	v_cvt_pk_bf16_f32 v164, v150, v151
	v_cvt_pk_bf16_f32 v165, v152, v153
	global_store_dwordx4 v212, v[162:165], s[100:101]
	global_load_dwordx4 v[110:113], v0, s[6:7]
	s_add_u32 s6, s6, 0x2000
	s_addc_u32 s7, s7, 0
	v_fmamk_f32 v146, v54, 0xbfb8aa3b, v138
	v_fmamk_f32 v147, v55, 0xbfb8aa3b, v139
	v_fmamk_f32 v148, v56, 0xbfb8aa3b, v140
	v_fmamk_f32 v149, v57, 0xbfb8aa3b, v141
	v_fmamk_f32 v150, v50, 0xbfb8aa3b, v142
	v_fmamk_f32 v151, v51, 0xbfb8aa3b, v143
	v_fmamk_f32 v152, v52, 0xbfb8aa3b, v144
	v_fmamk_f32 v153, v53, 0xbfb8aa3b, v145
	v_exp_f32_e32 v146, v146
	v_exp_f32_e32 v147, v147
	v_exp_f32_e32 v148, v148
	v_exp_f32_e32 v149, v149
	v_exp_f32_e32 v150, v150
	v_exp_f32_e32 v151, v151
	v_exp_f32_e32 v152, v152
	v_exp_f32_e32 v153, v153
	s_waitcnt vmcnt(10)
	v_lshlrev_b32_e32 v54, 16, v122
	v_and_b32_e32 v55, 0xffff0000, v122
	v_lshlrev_b32_e32 v56, 16, v123
	v_and_b32_e32 v57, 0xffff0000, v123
	v_lshlrev_b32_e32 v50, 16, v124
	v_and_b32_e32 v51, 0xffff0000, v124
	v_lshlrev_b32_e32 v52, 16, v125
	v_and_b32_e32 v53, 0xffff0000, v125
	v_add_f32_e32 v146, 1.0, v146
	v_add_f32_e32 v147, 1.0, v147
	v_add_f32_e32 v148, 1.0, v148
	v_add_f32_e32 v149, 1.0, v149
	v_add_f32_e32 v150, 1.0, v150
	v_add_f32_e32 v151, 1.0, v151
	v_add_f32_e32 v152, 1.0, v152
	v_add_f32_e32 v153, 1.0, v153
	v_rcp_f32_e32 v146, v146
	v_rcp_f32_e32 v147, v147
	v_rcp_f32_e32 v148, v148
	v_rcp_f32_e32 v149, v149
	v_rcp_f32_e32 v150, v150
	v_rcp_f32_e32 v151, v151
	v_rcp_f32_e32 v152, v152
	v_rcp_f32_e32 v153, v153
	v_pk_fma_f32 v[146:147], v[146:147], v[54:55], v[154:155]
	v_pk_fma_f32 v[148:149], v[148:149], v[56:57], v[154:155]
	v_pk_fma_f32 v[150:151], v[150:151], v[50:51], v[154:155]
	v_pk_fma_f32 v[152:153], v[152:153], v[52:53], v[154:155]
	v_cvt_pk_bf16_f32 v162, v146, v147
	v_cvt_pk_bf16_f32 v163, v148, v149
	v_cvt_pk_bf16_f32 v164, v150, v151
	v_cvt_pk_bf16_f32 v165, v152, v153
	global_store_dwordx4 v212, v[162:165], s[100:101] offset:256
	s_add_u32 s100, s100, 0x8000
	s_addc_u32 s101, s101, 0
	global_load_dwordx4 v[106:109], v0, s[6:7]
	v_fmamk_f32 v146, v46, 0xbfb8aa3b, v130
	v_fmamk_f32 v147, v47, 0xbfb8aa3b, v131
	v_fmamk_f32 v148, v48, 0xbfb8aa3b, v132
	v_fmamk_f32 v149, v49, 0xbfb8aa3b, v133
	v_fmamk_f32 v150, v42, 0xbfb8aa3b, v134
	v_fmamk_f32 v151, v43, 0xbfb8aa3b, v135
	v_fmamk_f32 v152, v44, 0xbfb8aa3b, v136
	v_fmamk_f32 v153, v45, 0xbfb8aa3b, v137
	v_exp_f32_e32 v146, v146
	v_exp_f32_e32 v147, v147
	v_exp_f32_e32 v148, v148
	v_exp_f32_e32 v149, v149
	v_exp_f32_e32 v150, v150
	v_exp_f32_e32 v151, v151
	v_exp_f32_e32 v152, v152
	v_exp_f32_e32 v153, v153
	s_waitcnt vmcnt(10)
; DI unsigned pack2(float a, float b) { fv2 v = {a, b}; return __builtin_bit_cast(unsigned, __builtin_convertvector(v, bfv2)); }
; DI float bflo(unsigned u) { return __uint_as_float(u << 16); }
; DI float bfhi(unsigned u) { return __uint_as_float(u & 0xffff0000u); }
; DI float sigmoidf_(float x) { return __builtin_amdgcn_rcpf(1.f + __expf(-x)); }
;   DI void operator()(const f32x4 (&acc)[2][2][4][2], const Unit& u, int wr, int wc, int fr, int fq) const {
;     ...
; #pragma unroll
;         for (int mm = 0; mm < 2; ++mm)
; #pragma unroll
;           for (int bj = 0; bj < 2; ++bj) {
;             const int m = mp * 2 + mm;
;             const f32x4 g0 = acc[ai][bj][m][0] + bv[bj][0], g1 = acc[ai][bj][m][1] + bv[bj][1];
;             const u32x4 p_ = pv[mm][bj], o_ = ov[mm][bj];
;             u32x4 w;
;             w.x = pack2(bflo(o_.x) + sigmoidf_(g0[0]) * bflo(p_.x), bfhi(o_.x) + sigmoidf_(g0[1]) * bfhi(p_.x));
;             w.y = pack2(bflo(o_.y) + sigmoidf_(g0[2]) * bflo(p_.y), bfhi(o_.y) + sigmoidf_(g0[3]) * bfhi(p_.y));
;             w.z = pack2(bflo(o_.z) + sigmoidf_(g1[0]) * bflo(p_.z), bfhi(o_.z) + sigmoidf_(g1[1]) * bfhi(p_.z));
;             w.w = pack2(bflo(o_.w) + sigmoidf_(g1[2]) * bflo(p_.w), bfhi(o_.w) + sigmoidf_(g1[3]) * bfhi(p_.w));
;             *(u32x4*)(mixed + (size_t)(row0 + ai * HALF + m * 16) * 1024 + col0 + bj * HALF) = w;
;           }
	v_lshlrev_b32_e32 v46, 16, v170
	v_and_b32_e32 v47, 0xffff0000, v170
	v_lshlrev_b32_e32 v48, 16, v171
	v_and_b32_e32 v49, 0xffff0000, v171
	v_lshlrev_b32_e32 v42, 16, v172
	v_and_b32_e32 v43, 0xffff0000, v172
	v_lshlrev_b32_e32 v44, 16, v173
	v_and_b32_e32 v45, 0xffff0000, v173
	v_add_f32_e32 v146, 1.0, v146
	v_add_f32_e32 v147, 1.0, v147
	v_add_f32_e32 v148, 1.0, v148
	v_add_f32_e32 v149, 1.0, v149
	v_add_f32_e32 v150, 1.0, v150
	v_add_f32_e32 v151, 1.0, v151
	v_add_f32_e32 v152, 1.0, v152
	v_add_f32_e32 v153, 1.0, v153
	v_rcp_f32_e32 v146, v146
	v_rcp_f32_e32 v147, v147
	v_rcp_f32_e32 v148, v148
	v_rcp_f32_e32 v149, v149
	v_rcp_f32_e32 v150, v150
	v_rcp_f32_e32 v151, v151
	v_rcp_f32_e32 v152, v152
	v_rcp_f32_e32 v153, v153
	v_pk_fma_f32 v[146:147], v[146:147], v[46:47], v[154:155]
	v_pk_fma_f32 v[148:149], v[148:149], v[48:49], v[154:155]
	v_pk_fma_f32 v[150:151], v[150:151], v[42:43], v[154:155]
	v_pk_fma_f32 v[152:153], v[152:153], v[44:45], v[154:155]
	v_cvt_pk_bf16_f32 v162, v146, v147
	v_cvt_pk_bf16_f32 v163, v148, v149
	v_cvt_pk_bf16_f32 v164, v150, v151
	v_cvt_pk_bf16_f32 v165, v152, v153
	global_store_dwordx4 v212, v[162:165], s[100:101]
	v_fmamk_f32 v146, v38, 0xbfb8aa3b, v138
	v_fmamk_f32 v147, v39, 0xbfb8aa3b, v139
	v_fmamk_f32 v148, v40, 0xbfb8aa3b, v140
	v_fmamk_f32 v149, v41, 0xbfb8aa3b, v141
	v_fmamk_f32 v150, v34, 0xbfb8aa3b, v142
	v_fmamk_f32 v151, v35, 0xbfb8aa3b, v143
	v_fmamk_f32 v152, v36, 0xbfb8aa3b, v144
	v_fmamk_f32 v153, v37, 0xbfb8aa3b, v145
	v_exp_f32_e32 v146, v146
	v_exp_f32_e32 v147, v147
	v_exp_f32_e32 v148, v148
	v_exp_f32_e32 v149, v149
	v_exp_f32_e32 v150, v150
	v_exp_f32_e32 v151, v151
	v_exp_f32_e32 v152, v152
	v_exp_f32_e32 v153, v153
	s_waitcnt vmcnt(9)
	v_lshlrev_b32_e32 v38, 16, v118
	v_and_b32_e32 v39, 0xffff0000, v118
	v_lshlrev_b32_e32 v40, 16, v119
	v_and_b32_e32 v41, 0xffff0000, v119
	v_lshlrev_b32_e32 v34, 16, v120
	v_and_b32_e32 v35, 0xffff0000, v120
	v_lshlrev_b32_e32 v36, 16, v121
	v_and_b32_e32 v37, 0xffff0000, v121
	v_add_f32_e32 v146, 1.0, v146
	v_add_f32_e32 v147, 1.0, v147
	v_add_f32_e32 v148, 1.0, v148
	v_add_f32_e32 v149, 1.0, v149
	v_add_f32_e32 v150, 1.0, v150
	v_add_f32_e32 v151, 1.0, v151
	v_add_f32_e32 v152, 1.0, v152
	v_add_f32_e32 v153, 1.0, v153
	v_rcp_f32_e32 v146, v146
	v_rcp_f32_e32 v147, v147
	v_rcp_f32_e32 v148, v148
	v_rcp_f32_e32 v149, v149
	v_rcp_f32_e32 v150, v150
	v_rcp_f32_e32 v151, v151
	v_rcp_f32_e32 v152, v152
	v_rcp_f32_e32 v153, v153
	v_pk_fma_f32 v[146:147], v[146:147], v[38:39], v[154:155]
	v_pk_fma_f32 v[148:149], v[148:149], v[40:41], v[154:155]
	v_pk_fma_f32 v[150:151], v[150:151], v[34:35], v[154:155]
	v_pk_fma_f32 v[152:153], v[152:153], v[36:37], v[154:155]
	v_cvt_pk_bf16_f32 v162, v146, v147
	v_cvt_pk_bf16_f32 v163, v148, v149
	v_cvt_pk_bf16_f32 v164, v150, v151
	v_cvt_pk_bf16_f32 v165, v152, v153
	global_store_dwordx4 v212, v[162:165], s[100:101] offset:256
	s_add_u32 s100, s100, 0x8000
	s_addc_u32 s101, s101, 0
	v_fmamk_f32 v146, v30, 0xbfb8aa3b, v130
	v_fmamk_f32 v147, v31, 0xbfb8aa3b, v131
	v_fmamk_f32 v148, v32, 0xbfb8aa3b, v132
	v_fmamk_f32 v149, v33, 0xbfb8aa3b, v133
	v_fmamk_f32 v150, v26, 0xbfb8aa3b, v134
	v_fmamk_f32 v151, v27, 0xbfb8aa3b, v135
	v_fmamk_f32 v152, v28, 0xbfb8aa3b, v136
	v_fmamk_f32 v153, v29, 0xbfb8aa3b, v137
	v_exp_f32_e32 v146, v146
	v_exp_f32_e32 v147, v147
	v_exp_f32_e32 v148, v148
	v_exp_f32_e32 v149, v149
	v_exp_f32_e32 v150, v150
	v_exp_f32_e32 v151, v151
	v_exp_f32_e32 v152, v152
	v_exp_f32_e32 v153, v153
	s_waitcnt vmcnt(8)
	v_lshlrev_b32_e32 v30, 16, v114
	v_and_b32_e32 v31, 0xffff0000, v114
	v_lshlrev_b32_e32 v32, 16, v115
	v_and_b32_e32 v33, 0xffff0000, v115
	v_lshlrev_b32_e32 v26, 16, v116
	v_and_b32_e32 v27, 0xffff0000, v116
	v_lshlrev_b32_e32 v28, 16, v117
	v_and_b32_e32 v29, 0xffff0000, v117
	v_add_f32_e32 v146, 1.0, v146
	v_add_f32_e32 v147, 1.0, v147
	v_add_f32_e32 v148, 1.0, v148
	v_add_f32_e32 v149, 1.0, v149
	v_add_f32_e32 v150, 1.0, v150
	v_add_f32_e32 v151, 1.0, v151
	v_add_f32_e32 v152, 1.0, v152
	v_add_f32_e32 v153, 1.0, v153
	v_rcp_f32_e32 v146, v146
	v_rcp_f32_e32 v147, v147
	v_rcp_f32_e32 v148, v148
	v_rcp_f32_e32 v149, v149
	v_rcp_f32_e32 v150, v150
	v_rcp_f32_e32 v151, v151
	v_rcp_f32_e32 v152, v152
	v_rcp_f32_e32 v153, v153
	v_pk_fma_f32 v[146:147], v[146:147], v[30:31], v[154:155]
	v_pk_fma_f32 v[148:149], v[148:149], v[32:33], v[154:155]
	v_pk_fma_f32 v[150:151], v[150:151], v[26:27], v[154:155]
	v_pk_fma_f32 v[152:153], v[152:153], v[28:29], v[154:155]
	v_cvt_pk_bf16_f32 v162, v146, v147
	v_cvt_pk_bf16_f32 v163, v148, v149
	v_cvt_pk_bf16_f32 v164, v150, v151
	v_cvt_pk_bf16_f32 v165, v152, v153
	global_store_dwordx4 v212, v[162:165], s[100:101]
	v_fmamk_f32 v146, v22, 0xbfb8aa3b, v138
	v_fmamk_f32 v147, v23, 0xbfb8aa3b, v139
	v_fmamk_f32 v148, v24, 0xbfb8aa3b, v140
	v_fmamk_f32 v149, v25, 0xbfb8aa3b, v141
	v_fmamk_f32 v150, v18, 0xbfb8aa3b, v142
	v_fmamk_f32 v151, v19, 0xbfb8aa3b, v143
	v_fmamk_f32 v152, v20, 0xbfb8aa3b, v144
	v_fmamk_f32 v153, v21, 0xbfb8aa3b, v145
	v_exp_f32_e32 v146, v146
	v_exp_f32_e32 v147, v147
	v_exp_f32_e32 v148, v148
	v_exp_f32_e32 v149, v149
	v_exp_f32_e32 v150, v150
	v_exp_f32_e32 v151, v151
	v_exp_f32_e32 v152, v152
	v_exp_f32_e32 v153, v153
	s_waitcnt vmcnt(7)
; DI unsigned pack2(float a, float b) { fv2 v = {a, b}; return __builtin_bit_cast(unsigned, __builtin_convertvector(v, bfv2)); }
; DI float bflo(unsigned u) { return __uint_as_float(u << 16); }
; DI float bfhi(unsigned u) { return __uint_as_float(u & 0xffff0000u); }
; DI float sigmoidf_(float x) { return __builtin_amdgcn_rcpf(1.f + __expf(-x)); }
;   DI void operator()(const f32x4 (&acc)[2][2][4][2], const Unit& u, int wr, int wc, int fr, int fq) const {
;     ...
; #pragma unroll
;         for (int mm = 0; mm < 2; ++mm)
; #pragma unroll
;           for (int bj = 0; bj < 2; ++bj) {
;             const int m = mp * 2 + mm;
;             const f32x4 g0 = acc[ai][bj][m][0] + bv[bj][0], g1 = acc[ai][bj][m][1] + bv[bj][1];
;             const u32x4 p_ = pv[mm][bj], o_ = ov[mm][bj];
;             u32x4 w;
;             w.x = pack2(bflo(o_.x) + sigmoidf_(g0[0]) * bflo(p_.x), bfhi(o_.x) + sigmoidf_(g0[1]) * bfhi(p_.x));
;             w.y = pack2(bflo(o_.y) + sigmoidf_(g0[2]) * bflo(p_.y), bfhi(o_.y) + sigmoidf_(g0[3]) * bfhi(p_.y));
;             w.z = pack2(bflo(o_.z) + sigmoidf_(g1[0]) * bflo(p_.z), bfhi(o_.z) + sigmoidf_(g1[1]) * bfhi(p_.z));
;             w.w = pack2(bflo(o_.w) + sigmoidf_(g1[2]) * bflo(p_.w), bfhi(o_.w) + sigmoidf_(g1[3]) * bfhi(p_.w));
;             *(u32x4*)(mixed + (size_t)(row0 + ai * HALF + m * 16) * 1024 + col0 + bj * HALF) = w;
;           }
	v_lshlrev_b32_e32 v22, 16, v174
	v_and_b32_e32 v23, 0xffff0000, v174
	v_lshlrev_b32_e32 v24, 16, v175
	v_and_b32_e32 v25, 0xffff0000, v175
	v_lshlrev_b32_e32 v18, 16, v176
	v_and_b32_e32 v19, 0xffff0000, v176
	v_lshlrev_b32_e32 v20, 16, v177
	v_and_b32_e32 v21, 0xffff0000, v177
	v_add_f32_e32 v146, 1.0, v146
	v_add_f32_e32 v147, 1.0, v147
	v_add_f32_e32 v148, 1.0, v148
	v_add_f32_e32 v149, 1.0, v149
	v_add_f32_e32 v150, 1.0, v150
	v_add_f32_e32 v151, 1.0, v151
	v_add_f32_e32 v152, 1.0, v152
	v_add_f32_e32 v153, 1.0, v153
	v_rcp_f32_e32 v146, v146
	v_rcp_f32_e32 v147, v147
	v_rcp_f32_e32 v148, v148
	v_rcp_f32_e32 v149, v149
	v_rcp_f32_e32 v150, v150
	v_rcp_f32_e32 v151, v151
	v_rcp_f32_e32 v152, v152
	v_rcp_f32_e32 v153, v153
	v_pk_fma_f32 v[146:147], v[146:147], v[22:23], v[154:155]
	v_pk_fma_f32 v[148:149], v[148:149], v[24:25], v[154:155]
	v_pk_fma_f32 v[150:151], v[150:151], v[18:19], v[154:155]
	v_pk_fma_f32 v[152:153], v[152:153], v[20:21], v[154:155]
	v_cvt_pk_bf16_f32 v162, v146, v147
	v_cvt_pk_bf16_f32 v163, v148, v149
	v_cvt_pk_bf16_f32 v164, v150, v151
	v_cvt_pk_bf16_f32 v165, v152, v153
	global_store_dwordx4 v212, v[162:165], s[100:101] offset:256
	s_add_u32 s100, s100, 0x8000
	s_addc_u32 s101, s101, 0
	v_fmamk_f32 v146, v14, 0xbfb8aa3b, v130
	v_fmamk_f32 v147, v15, 0xbfb8aa3b, v131
	v_fmamk_f32 v148, v16, 0xbfb8aa3b, v132
	v_fmamk_f32 v149, v17, 0xbfb8aa3b, v133
	v_fmamk_f32 v150, v10, 0xbfb8aa3b, v134
	v_fmamk_f32 v151, v11, 0xbfb8aa3b, v135
	v_fmamk_f32 v152, v12, 0xbfb8aa3b, v136
	v_fmamk_f32 v153, v13, 0xbfb8aa3b, v137
	v_exp_f32_e32 v146, v146
	v_exp_f32_e32 v147, v147
	v_exp_f32_e32 v148, v148
	v_exp_f32_e32 v149, v149
	v_exp_f32_e32 v150, v150
	v_exp_f32_e32 v151, v151
	v_exp_f32_e32 v152, v152
	v_exp_f32_e32 v153, v153
	s_waitcnt vmcnt(6)
	v_lshlrev_b32_e32 v14, 16, v110
	v_and_b32_e32 v15, 0xffff0000, v110
	v_lshlrev_b32_e32 v16, 16, v111
	v_and_b32_e32 v17, 0xffff0000, v111
	v_lshlrev_b32_e32 v10, 16, v112
	v_and_b32_e32 v11, 0xffff0000, v112
	v_lshlrev_b32_e32 v12, 16, v113
	v_and_b32_e32 v13, 0xffff0000, v113
	v_add_f32_e32 v146, 1.0, v146
	v_add_f32_e32 v147, 1.0, v147
	v_add_f32_e32 v148, 1.0, v148
	v_add_f32_e32 v149, 1.0, v149
	v_add_f32_e32 v150, 1.0, v150
	v_add_f32_e32 v151, 1.0, v151
	v_add_f32_e32 v152, 1.0, v152
	v_add_f32_e32 v153, 1.0, v153
	v_rcp_f32_e32 v146, v146
	v_rcp_f32_e32 v147, v147
	v_rcp_f32_e32 v148, v148
	v_rcp_f32_e32 v149, v149
	v_rcp_f32_e32 v150, v150
	v_rcp_f32_e32 v151, v151
	v_rcp_f32_e32 v152, v152
	v_rcp_f32_e32 v153, v153
	v_pk_fma_f32 v[146:147], v[146:147], v[14:15], v[154:155]
	v_pk_fma_f32 v[148:149], v[148:149], v[16:17], v[154:155]
	v_pk_fma_f32 v[150:151], v[150:151], v[10:11], v[154:155]
	v_pk_fma_f32 v[152:153], v[152:153], v[12:13], v[154:155]
	v_cvt_pk_bf16_f32 v162, v146, v147
	v_cvt_pk_bf16_f32 v163, v148, v149
	v_cvt_pk_bf16_f32 v164, v150, v151
	v_cvt_pk_bf16_f32 v165, v152, v153
	global_store_dwordx4 v212, v[162:165], s[100:101]
	v_fmamk_f32 v146, v6, 0xbfb8aa3b, v138
	v_fmamk_f32 v147, v7, 0xbfb8aa3b, v139
	v_fmamk_f32 v148, v8, 0xbfb8aa3b, v140
	v_fmamk_f32 v149, v9, 0xbfb8aa3b, v141
	v_fmamk_f32 v150, v2, 0xbfb8aa3b, v142
	v_fmamk_f32 v151, v3, 0xbfb8aa3b, v143
	v_fmamk_f32 v152, v4, 0xbfb8aa3b, v144
	v_fmamk_f32 v153, v5, 0xbfb8aa3b, v145
	v_exp_f32_e32 v146, v146
	v_exp_f32_e32 v147, v147
	v_exp_f32_e32 v148, v148
	v_exp_f32_e32 v149, v149
	v_exp_f32_e32 v150, v150
	v_exp_f32_e32 v151, v151
	v_exp_f32_e32 v152, v152
	v_exp_f32_e32 v153, v153
	s_waitcnt vmcnt(5)
	v_lshlrev_b32_e32 v6, 16, v106
	v_and_b32_e32 v7, 0xffff0000, v106
	v_lshlrev_b32_e32 v8, 16, v107
	v_and_b32_e32 v9, 0xffff0000, v107
	v_lshlrev_b32_e32 v2, 16, v108
	v_and_b32_e32 v3, 0xffff0000, v108
	v_lshlrev_b32_e32 v4, 16, v109
	v_and_b32_e32 v5, 0xffff0000, v109
	v_add_f32_e32 v146, 1.0, v146
	v_add_f32_e32 v147, 1.0, v147
	v_add_f32_e32 v148, 1.0, v148
	v_add_f32_e32 v149, 1.0, v149
	v_add_f32_e32 v150, 1.0, v150
	v_add_f32_e32 v151, 1.0, v151
	v_add_f32_e32 v152, 1.0, v152
	v_add_f32_e32 v153, 1.0, v153
	v_rcp_f32_e32 v146, v146
	v_rcp_f32_e32 v147, v147
	v_rcp_f32_e32 v148, v148
	v_rcp_f32_e32 v149, v149
	v_rcp_f32_e32 v150, v150
	v_rcp_f32_e32 v151, v151
	v_rcp_f32_e32 v152, v152
	v_rcp_f32_e32 v153, v153
	v_pk_fma_f32 v[146:147], v[146:147], v[6:7], v[154:155]
	v_pk_fma_f32 v[148:149], v[148:149], v[8:9], v[154:155]
	v_pk_fma_f32 v[150:151], v[150:151], v[2:3], v[154:155]
	v_pk_fma_f32 v[152:153], v[152:153], v[4:5], v[154:155]
	v_cvt_pk_bf16_f32 v162, v146, v147
	v_cvt_pk_bf16_f32 v163, v148, v149
	v_cvt_pk_bf16_f32 v164, v150, v151
	v_cvt_pk_bf16_f32 v165, v152, v153
	global_store_dwordx4 v212, v[162:165], s[100:101] offset:256
	s_branch .LBB0_930
